# GEMM phases 1/4/8/12: epilogue row-statistic loads hoisted to tile start (spare VGPRs), epilogue-head vmcnt(0) drain removed
# speedup vs baseline: 1.0101x; 1.0017x over previous
; #define PG8_STAGE(bufoff, gbase, voff) do { _Pragma("unroll") for (int _i = 0; _i < 2; ++_i) \
;         __builtin_amdgcn_global_load_lds((const unsigned*)((const char*)(gbase) + (voff)[_i]), (LAS unsigned*)(lds + (bufoff) + ldsw + _i * 8192), 16, 0, 0); } while (0)
; #define PG8_LDA(dst, b, h) do { _Pragma("unroll") for (int m = 0; m < 4; ++m) _Pragma("unroll") for (int k = 0; k < 2; ++k) dst[m][k] = *(const LAS bf16x8*)(lds + PG8_SA(b, h) + aoff + m * 2048 + k * 1024); } while (0)
; #define PG8_LDB(dst, b, h) do { _Pragma("unroll") for (int n = 0; n < 2; ++n) _Pragma("unroll") for (int k = 0; k < 2; ++k) dst[n][k] = *(const LAS bf16x8*)(lds + PG8_SB(b, h) + boff + n * 2048 + k * 1024); } while (0)
; #define PG8_MMA(ai, bj, At, Bt) do { __builtin_amdgcn_s_setprio(1); _Pragma("unroll") for (int m = 0; m < 4; ++m) _Pragma("unroll") for (int n = 0; n < 2; ++n) _Pragma("unroll") for (int k = 0; k < 2; ++k) \
;         acc[ai][bj][m][n] = __builtin_amdgcn_mfma_f32_16x16x32_bf16(Bt[n][k], At[m][k], acc[ai][bj][m][n], 0, 0, 0); __builtin_amdgcn_s_setprio(0); } while (0)
; #define PG8_BAR __builtin_amdgcn_s_barrier()
; template <class Epi>
; __device__ __forceinline__ void gemm_phase(LAS unsigned char* lds, const Gemm g, const StaticOrder& S, const Epi& E) {
;     ...
;         const bool has_next = S.next(ui + 1, nxt);
;         const char* nA = has_next ? (const char*)g.A + (size_t)nxt.pm * tstepA : cA; const char* nB = has_next ? (const char*)g.Bt + (size_t)nxt.pn * tstepB : cB;
; #pragma nounroll
;         for (int t = 0; t < nt; t += 2) {
;             const bool last = (t == nt - 2);
;             const char* a1 = cA + (size_t)(t + 1) * kstep;
;             const char* a2 = last ? nA : cA + (size_t)(t + 2) * kstep; const char* b2 = last ? nB : cB + (size_t)(t + 2) * kstep;
;             const char* a3 = a2 + kstep; const char* b3 = b2 + kstep;
;             PG8_LDB(B0, 0, 0); PG8_LDB(B1, 0, 1); PG8_SCHED; PG8_LDA(At, 0, 0); PG8_STAGE(PG8_SA(1, 1), a1 + hstepA, voffA);
;             PG8_WAIT_V(8); PG8_WAIT_L(0); PG8_BAR; PG8_MMA(0, 0, At, B0); PG8_MMA(0, 1, At, B1); PG8_BAR; PG8_SCHED;
;             PG8_LDA(At, 0, 1); PG8_STAGE(PG8_SB(0, 0), b2, voffB); PG8_STAGE(PG8_SB(0, 1), b2 + hstepB, voffB); PG8_STAGE(PG8_SA(0, 0), a2, voffA);
;             PG8_WAIT_V(8); PG8_WAIT_L(0); PG8_BAR; PG8_MMA(1, 0, At, B0); PG8_MMA(1, 1, At, B1); PG8_BAR; PG8_SCHED;
.LBB0_191:
	s_ashr_i32 s65, s64, 31
	s_lshl_b64 s[68:69], s[64:65], 19
	s_add_u32 s68, s24, s68
	s_addc_u32 s69, s25, s69
	s_and_b64 s[70:71], s[4:5], exec
	s_cselect_b32 s7, s69, s75
	s_cselect_b32 s65, s68, s74
	s_ashr_i32 s63, s62, 31
	s_lshl_b64 s[70:71], s[62:63], 19
	s_add_u32 s70, s10, s70
	s_addc_u32 s71, s11, s71
	s_and_b64 s[78:79], s[4:5], exec
	s_cselect_b32 s63, s71, s77
	s_cselect_b32 s73, s70, s76
	s_add_u32 s74, s74, 0x40080
	s_addc_u32 s75, s75, 0
	s_add_u32 s87, s76, 0x100
	s_addc_u32 s88, s77, 0
	s_mov_b32 s89, -2
	v_lshl_add_u32 v248, s72, 8, v150
	v_add_u32_e32 v248, s41, v248
	v_ashrrev_i32_e32 v249, 31, v248
	v_lshl_add_u64 v[248:249], v[248:249], 2, s[50:51]
	global_load_dword v240, v[248:249], off
	global_load_dword v241, v[248:249], off offset:64
	global_load_dword v242, v[248:249], off offset:128
	global_load_dword v243, v[248:249], off offset:192
	global_load_dword v244, v[248:249], off offset:512
	global_load_dword v245, v[248:249], off offset:576
	global_load_dword v246, v[248:249], off offset:640
	global_load_dword v247, v[248:249], off offset:704
	ds_read_b128 v[144:147], v153
	ds_read_b128 v[158:161], v153 offset:1024
	ds_read_b128 v[162:165], v153 offset:2048
	ds_read_b128 v[166:169], v153 offset:3072
	ds_read_b128 v[170:173], v154
	ds_read_b128 v[178:181], v154 offset:1024
	ds_read_b128 v[182:185], v154 offset:2048
	ds_read_b128 v[186:189], v154 offset:3072
	s_add_u32 s76, s74, 0xfffc0080
	s_addc_u32 s77, s75, -1
	s_cmp_eq_u32 s89, 12
	s_cselect_b32 s79, s7, s77
	s_cselect_b32 s78, s65, s76
	s_cselect_b32 s77, s63, s88
	s_cselect_b32 s76, s73, s87
	v_lshl_add_u64 v[148:149], s[74:75], 0, v[136:137]
	s_add_i32 m0, s19, 0xc000
	ds_read_b128 v[190:193], v155
	ds_read_b128 v[194:197], v155 offset:1024
	ds_read_b128 v[198:201], v155 offset:2048
	ds_read_b128 v[202:205], v155 offset:3072
	ds_read_b128 v[206:209], v155 offset:4096
	ds_read_b128 v[210:213], v155 offset:5120
	ds_read_b128 v[214:217], v155 offset:6144
	ds_read_b128 v[218:221], v155 offset:7168
	global_load_lds_dwordx4 v[148:149], off
	v_lshl_add_u64 v[148:149], s[74:75], 0, v[138:139]
	s_add_i32 m0, s19, 0xe000
	s_nop 0
	global_load_lds_dwordx4 v[148:149], off
	s_waitcnt vmcnt(8)
	s_waitcnt lgkmcnt(0)
	s_barrier
	s_setprio 1
	s_waitcnt lgkmcnt(0)
	v_mfma_f32_16x16x32_bf16 v[124:127], v[144:147], v[190:193], 0
	v_mfma_f32_16x16x32_bf16 v[120:123], v[162:165], v[190:193], 0
	v_mfma_f32_16x16x32_bf16 v[108:111], v[144:147], v[198:201], 0
	v_mfma_f32_16x16x32_bf16 v[104:107], v[162:165], v[198:201], 0
	v_mfma_f32_16x16x32_bf16 v[92:95], v[144:147], v[206:209], 0
	v_mfma_f32_16x16x32_bf16 v[88:91], v[162:165], v[206:209], 0
	v_mfma_f32_16x16x32_bf16 v[76:79], v[144:147], v[214:217], 0
	v_mfma_f32_16x16x32_bf16 v[72:75], v[162:165], v[214:217], 0
	v_mfma_f32_16x16x32_bf16 v[124:127], v[158:161], v[194:197], v[124:127]
	v_mfma_f32_16x16x32_bf16 v[120:123], v[166:169], v[194:197], v[120:123]
	v_mfma_f32_16x16x32_bf16 v[108:111], v[158:161], v[202:205], v[108:111]
	v_mfma_f32_16x16x32_bf16 v[104:107], v[166:169], v[202:205], v[104:107]
	v_mfma_f32_16x16x32_bf16 v[92:95], v[158:161], v[210:213], v[92:95]
	v_mfma_f32_16x16x32_bf16 v[88:91], v[166:169], v[210:213], v[88:91]
	v_mfma_f32_16x16x32_bf16 v[76:79], v[158:161], v[218:221], v[76:79]
	v_mfma_f32_16x16x32_bf16 v[72:75], v[166:169], v[218:221], v[72:75]
	s_setprio 0
	s_setprio 1
	v_mfma_f32_16x16x32_bf16 v[116:119], v[170:173], v[190:193], 0
	v_mfma_f32_16x16x32_bf16 v[112:115], v[182:185], v[190:193], 0
	v_mfma_f32_16x16x32_bf16 v[100:103], v[170:173], v[198:201], 0
	v_mfma_f32_16x16x32_bf16 v[96:99], v[182:185], v[198:201], 0
	v_mfma_f32_16x16x32_bf16 v[84:87], v[170:173], v[206:209], 0
	v_mfma_f32_16x16x32_bf16 v[80:83], v[182:185], v[206:209], 0
	v_mfma_f32_16x16x32_bf16 v[68:71], v[170:173], v[214:217], 0
	v_mfma_f32_16x16x32_bf16 v[64:67], v[182:185], v[214:217], 0
	v_mfma_f32_16x16x32_bf16 v[116:119], v[178:181], v[194:197], v[116:119]
	v_mfma_f32_16x16x32_bf16 v[112:115], v[186:189], v[194:197], v[112:115]
	v_mfma_f32_16x16x32_bf16 v[100:103], v[178:181], v[202:205], v[100:103]
	v_mfma_f32_16x16x32_bf16 v[96:99], v[186:189], v[202:205], v[96:99]
	v_mfma_f32_16x16x32_bf16 v[84:87], v[178:181], v[210:213], v[84:87]
	v_mfma_f32_16x16x32_bf16 v[80:83], v[186:189], v[210:213], v[80:83]
	v_mfma_f32_16x16x32_bf16 v[68:71], v[178:181], v[218:221], v[68:71]
	v_mfma_f32_16x16x32_bf16 v[64:67], v[186:189], v[218:221], v[64:67]
	s_setprio 0
	s_barrier
	s_add_i32 s90, s84, s3
	v_lshl_add_u64 v[148:149], s[76:77], 0, v[130:131]
	s_mov_b32 m0, s90
	ds_read_b128 v[190:193], v155 offset:16384
	ds_read_b128 v[194:197], v155 offset:17408
	ds_read_b128 v[198:201], v155 offset:18432
	ds_read_b128 v[202:205], v155 offset:19456
	ds_read_b128 v[206:209], v155 offset:20480
	ds_read_b128 v[210:213], v155 offset:21504
	ds_read_b128 v[214:217], v155 offset:22528
	ds_read_b128 v[218:221], v155 offset:23552
	global_load_lds_dwordx4 v[148:149], off
	s_add_i32 m0, s90, 0x2000
	s_add_u32 s90, s76, 0x40000
	v_lshl_add_u64 v[174:175], s[76:77], 0, v[134:135]
	s_addc_u32 s91, s77, 0
	s_add_i32 s92, s85, s3
	global_load_lds_dwordx4 v[174:175], off
	v_lshl_add_u64 v[222:223], s[90:91], 0, v[130:131]
	s_mov_b32 m0, s92
	v_lshl_add_u64 v[226:227], s[78:79], 0, v[132:133]
	global_load_lds_dwordx4 v[222:223], off
	v_lshl_add_u64 v[222:223], s[90:91], 0, v[134:135]
	s_add_i32 m0, s92, 0x2000
	s_nop 0
	global_load_lds_dwordx4 v[222:223], off
	v_lshl_add_u64 v[222:223], s[78:79], 0, v[128:129]
	s_mov_b32 m0, s19
	s_nop 0
	global_load_lds_dwordx4 v[222:223], off
	s_mov_b32 m0, s23
	s_nop 0
	global_load_lds_dwordx4 v[226:227], off
	s_waitcnt vmcnt(8)
	s_waitcnt lgkmcnt(0)
	s_barrier
; #define PG8_STAGE(bufoff, gbase, voff) do { _Pragma("unroll") for (int _i = 0; _i < 2; ++_i) \
;         __builtin_amdgcn_global_load_lds((const unsigned*)((const char*)(gbase) + (voff)[_i]), (LAS unsigned*)(lds + (bufoff) + ldsw + _i * 8192), 16, 0, 0); } while (0)
; #define PG8_LDA(dst, b, h) do { _Pragma("unroll") for (int m = 0; m < 4; ++m) _Pragma("unroll") for (int k = 0; k < 2; ++k) dst[m][k] = *(const LAS bf16x8*)(lds + PG8_SA(b, h) + aoff + m * 2048 + k * 1024); } while (0)
; #define PG8_LDB(dst, b, h) do { _Pragma("unroll") for (int n = 0; n < 2; ++n) _Pragma("unroll") for (int k = 0; k < 2; ++k) dst[n][k] = *(const LAS bf16x8*)(lds + PG8_SB(b, h) + boff + n * 2048 + k * 1024); } while (0)
; #define PG8_MMA(ai, bj, At, Bt) do { __builtin_amdgcn_s_setprio(1); _Pragma("unroll") for (int m = 0; m < 4; ++m) _Pragma("unroll") for (int n = 0; n < 2; ++n) _Pragma("unroll") for (int k = 0; k < 2; ++k) \
;         acc[ai][bj][m][n] = __builtin_amdgcn_mfma_f32_16x16x32_bf16(Bt[n][k], At[m][k], acc[ai][bj][m][n], 0, 0, 0); __builtin_amdgcn_s_setprio(0); } while (0)
; #define PG8_WAIT_V(n) asm volatile("s_waitcnt vmcnt(" #n ")" ::: "memory")
; #define PG8_WAIT_L(n) asm volatile("s_waitcnt lgkmcnt(" #n ")" ::: "memory")
; #define PG8_BAR __builtin_amdgcn_s_barrier()
; #define PG8_SCHED __builtin_amdgcn_sched_barrier(0)
; template <class Epi>
; __device__ __forceinline__ void gemm_phase(LAS unsigned char* lds, const Gemm g, const StaticOrder& S, const Epi& E) {
;     ...
;             PG8_WAIT_V(8); PG8_WAIT_L(0); PG8_BAR; PG8_MMA(1, 0, At, B0); PG8_MMA(1, 1, At, B1); PG8_BAR; PG8_SCHED;
;             PG8_LDB(B0, 1, 0); PG8_LDB(B1, 1, 1); PG8_SCHED; PG8_LDA(At, 1, 0); PG8_STAGE(PG8_SA(0, 1), a2 + hstepA, voffA);
;             PG8_WAIT_V(8); PG8_WAIT_L(0); PG8_BAR; PG8_MMA(0, 0, At, B0); PG8_MMA(0, 1, At, B1); PG8_BAR; PG8_SCHED;
;             PG8_LDA(At, 1, 1); PG8_STAGE(PG8_SB(1, 0), b3, voffB); PG8_STAGE(PG8_SB(1, 1), b3 + hstepB, voffB); PG8_STAGE(PG8_SA(1, 0), a3, voffA);
	s_setprio 1
	s_waitcnt lgkmcnt(0)
	v_mfma_f32_16x16x32_bf16 v[60:63], v[144:147], v[190:193], 0
	v_mfma_f32_16x16x32_bf16 v[56:59], v[162:165], v[190:193], 0
	v_mfma_f32_16x16x32_bf16 v[44:47], v[144:147], v[198:201], 0
	v_mfma_f32_16x16x32_bf16 v[40:43], v[162:165], v[198:201], 0
	v_mfma_f32_16x16x32_bf16 v[28:31], v[144:147], v[206:209], 0
	v_mfma_f32_16x16x32_bf16 v[24:27], v[162:165], v[206:209], 0
	v_mfma_f32_16x16x32_bf16 v[12:15], v[144:147], v[214:217], 0
	v_mfma_f32_16x16x32_bf16 v[8:11], v[162:165], v[214:217], 0
	v_mfma_f32_16x16x32_bf16 v[60:63], v[158:161], v[194:197], v[60:63]
	v_mfma_f32_16x16x32_bf16 v[56:59], v[166:169], v[194:197], v[56:59]
	v_mfma_f32_16x16x32_bf16 v[44:47], v[158:161], v[202:205], v[44:47]
	v_mfma_f32_16x16x32_bf16 v[40:43], v[166:169], v[202:205], v[40:43]
	v_mfma_f32_16x16x32_bf16 v[28:31], v[158:161], v[210:213], v[28:31]
	v_mfma_f32_16x16x32_bf16 v[24:27], v[166:169], v[210:213], v[24:27]
	v_mfma_f32_16x16x32_bf16 v[12:15], v[158:161], v[218:221], v[12:15]
	v_mfma_f32_16x16x32_bf16 v[8:11], v[166:169], v[218:221], v[8:11]
	s_setprio 0
	s_setprio 1
	v_mfma_f32_16x16x32_bf16 v[52:55], v[170:173], v[190:193], 0
	v_mfma_f32_16x16x32_bf16 v[48:51], v[182:185], v[190:193], 0
	v_mfma_f32_16x16x32_bf16 v[36:39], v[170:173], v[198:201], 0
	v_mfma_f32_16x16x32_bf16 v[32:35], v[182:185], v[198:201], 0
	v_mfma_f32_16x16x32_bf16 v[20:23], v[170:173], v[206:209], 0
	v_mfma_f32_16x16x32_bf16 v[16:19], v[182:185], v[206:209], 0
	v_mfma_f32_16x16x32_bf16 v[4:7], v[170:173], v[214:217], 0
	v_mfma_f32_16x16x32_bf16 v[0:3], v[182:185], v[214:217], 0
	v_mfma_f32_16x16x32_bf16 v[52:55], v[178:181], v[194:197], v[52:55]
	v_mfma_f32_16x16x32_bf16 v[48:51], v[186:189], v[194:197], v[48:51]
	v_mfma_f32_16x16x32_bf16 v[36:39], v[178:181], v[202:205], v[36:39]
	v_mfma_f32_16x16x32_bf16 v[32:35], v[186:189], v[202:205], v[32:35]
	v_mfma_f32_16x16x32_bf16 v[20:23], v[178:181], v[210:213], v[20:23]
	v_mfma_f32_16x16x32_bf16 v[16:19], v[186:189], v[210:213], v[16:19]
	v_mfma_f32_16x16x32_bf16 v[4:7], v[178:181], v[218:221], v[4:7]
	v_mfma_f32_16x16x32_bf16 v[0:3], v[186:189], v[218:221], v[0:3]
	s_setprio 0
	s_barrier
	s_add_i32 s90, 0, 0x18000
	v_add_u32_e32 v157, s90, v152
	s_add_i32 s91, 0, 0x1c000
	ds_read_b128 v[144:147], v157
	ds_read_b128 v[158:161], v157 offset:1024
	ds_read_b128 v[162:165], v157 offset:2048
	ds_read_b128 v[166:169], v157 offset:3072
	v_add_u32_e32 v157, s91, v152
	ds_read_b128 v[170:173], v157
	ds_read_b128 v[178:181], v157 offset:1024
	ds_read_b128 v[182:185], v157 offset:2048
	ds_read_b128 v[186:189], v157 offset:3072
	s_add_u32 s78, s78, 0x40000
	s_addc_u32 s79, s79, 0
	s_mov_b32 m0, s33
	v_lshl_add_u64 v[228:229], s[78:79], 0, v[128:129]
	ds_read_b128 v[190:193], v155 offset:32768
	ds_read_b128 v[194:197], v155 offset:33792
	ds_read_b128 v[198:201], v155 offset:34816
	ds_read_b128 v[202:205], v155 offset:35840
	ds_read_b128 v[206:209], v155 offset:36864
	ds_read_b128 v[210:213], v155 offset:37888
	ds_read_b128 v[214:217], v155 offset:38912
	ds_read_b128 v[218:221], v155 offset:39936
	global_load_lds_dwordx4 v[228:229], off
	v_lshl_add_u64 v[228:229], s[78:79], 0, v[132:133]
	s_mov_b32 m0, s35
	s_nop 0
	global_load_lds_dwordx4 v[228:229], off
	s_waitcnt vmcnt(8)
	s_waitcnt lgkmcnt(0)
	s_barrier
	s_setprio 1
	s_waitcnt lgkmcnt(0)
	v_mfma_f32_16x16x32_bf16 v[124:127], v[144:147], v[190:193], v[124:127]
	v_mfma_f32_16x16x32_bf16 v[120:123], v[162:165], v[190:193], v[120:123]
	v_mfma_f32_16x16x32_bf16 v[108:111], v[144:147], v[198:201], v[108:111]
	v_mfma_f32_16x16x32_bf16 v[104:107], v[162:165], v[198:201], v[104:107]
	v_mfma_f32_16x16x32_bf16 v[92:95], v[144:147], v[206:209], v[92:95]
	v_mfma_f32_16x16x32_bf16 v[88:91], v[162:165], v[206:209], v[88:91]
	v_mfma_f32_16x16x32_bf16 v[76:79], v[144:147], v[214:217], v[76:79]
	v_mfma_f32_16x16x32_bf16 v[72:75], v[162:165], v[214:217], v[72:75]
	v_mfma_f32_16x16x32_bf16 v[124:127], v[158:161], v[194:197], v[124:127]
	v_mfma_f32_16x16x32_bf16 v[120:123], v[166:169], v[194:197], v[120:123]
	v_mfma_f32_16x16x32_bf16 v[108:111], v[158:161], v[202:205], v[108:111]
	v_mfma_f32_16x16x32_bf16 v[104:107], v[166:169], v[202:205], v[104:107]
	v_mfma_f32_16x16x32_bf16 v[92:95], v[158:161], v[210:213], v[92:95]
	v_mfma_f32_16x16x32_bf16 v[88:91], v[166:169], v[210:213], v[88:91]
	v_mfma_f32_16x16x32_bf16 v[76:79], v[158:161], v[218:221], v[76:79]
	v_mfma_f32_16x16x32_bf16 v[72:75], v[166:169], v[218:221], v[72:75]
	s_setprio 0
	s_setprio 1
	v_mfma_f32_16x16x32_bf16 v[116:119], v[170:173], v[190:193], v[116:119]
	v_mfma_f32_16x16x32_bf16 v[112:115], v[182:185], v[190:193], v[112:115]
	v_mfma_f32_16x16x32_bf16 v[100:103], v[170:173], v[198:201], v[100:103]
	v_mfma_f32_16x16x32_bf16 v[96:99], v[182:185], v[198:201], v[96:99]
	v_mfma_f32_16x16x32_bf16 v[84:87], v[170:173], v[206:209], v[84:87]
	v_mfma_f32_16x16x32_bf16 v[80:83], v[182:185], v[206:209], v[80:83]
	v_mfma_f32_16x16x32_bf16 v[68:71], v[170:173], v[214:217], v[68:71]
	v_mfma_f32_16x16x32_bf16 v[64:67], v[182:185], v[214:217], v[64:67]
	v_mfma_f32_16x16x32_bf16 v[116:119], v[178:181], v[194:197], v[116:119]
	v_mfma_f32_16x16x32_bf16 v[112:115], v[186:189], v[194:197], v[112:115]
	v_mfma_f32_16x16x32_bf16 v[100:103], v[178:181], v[202:205], v[100:103]
	v_mfma_f32_16x16x32_bf16 v[96:99], v[186:189], v[202:205], v[96:99]
	v_mfma_f32_16x16x32_bf16 v[84:87], v[178:181], v[210:213], v[84:87]
	v_mfma_f32_16x16x32_bf16 v[80:83], v[186:189], v[210:213], v[80:83]
	v_mfma_f32_16x16x32_bf16 v[68:71], v[178:181], v[218:221], v[68:71]
	v_mfma_f32_16x16x32_bf16 v[64:67], v[186:189], v[218:221], v[64:67]
	s_setprio 0
	s_barrier
; #define PG8_STAGE(bufoff, gbase, voff) do { _Pragma("unroll") for (int _i = 0; _i < 2; ++_i) \
;         __builtin_amdgcn_global_load_lds((const unsigned*)((const char*)(gbase) + (voff)[_i]), (LAS unsigned*)(lds + (bufoff) + ldsw + _i * 8192), 16, 0, 0); } while (0)
; #define PG8_LDA(dst, b, h) do { _Pragma("unroll") for (int m = 0; m < 4; ++m) _Pragma("unroll") for (int k = 0; k < 2; ++k) dst[m][k] = *(const LAS bf16x8*)(lds + PG8_SA(b, h) + aoff + m * 2048 + k * 1024); } while (0)
; #define PG8_LDB(dst, b, h) do { _Pragma("unroll") for (int n = 0; n < 2; ++n) _Pragma("unroll") for (int k = 0; k < 2; ++k) dst[n][k] = *(const LAS bf16x8*)(lds + PG8_SB(b, h) + boff + n * 2048 + k * 1024); } while (0)
; #define PG8_WAIT_V(n) asm volatile("s_waitcnt vmcnt(" #n ")" ::: "memory")
; #define PG8_WAIT_L(n) asm volatile("s_waitcnt lgkmcnt(" #n ")" ::: "memory")
; template <class Epi>
; __device__ __forceinline__ void gemm_phase(LAS unsigned char* lds, const Gemm g, const StaticOrder& S, const Epi& E) {
;     ...
;         for (int t = 0; t < nt; t += 2) {
;             const bool last = (t == nt - 2);
;             const char* a1 = cA + (size_t)(t + 1) * kstep;
;             const char* a2 = last ? nA : cA + (size_t)(t + 2) * kstep; const char* b2 = last ? nB : cB + (size_t)(t + 2) * kstep;
;             const char* a3 = a2 + kstep; const char* b3 = b2 + kstep;
;             PG8_LDB(B0, 0, 0); PG8_LDB(B1, 0, 1); PG8_SCHED; PG8_LDA(At, 0, 0); PG8_STAGE(PG8_SA(1, 1), a1 + hstepA, voffA);
;             PG8_WAIT_V(8); PG8_WAIT_L(0); PG8_BAR; PG8_MMA(0, 0, At, B0); PG8_MMA(0, 1, At, B1); PG8_BAR; PG8_SCHED;
;             PG8_LDA(At, 0, 1); PG8_STAGE(PG8_SB(0, 0), b2, voffB); PG8_STAGE(PG8_SB(0, 1), b2 + hstepB, voffB); PG8_STAGE(PG8_SA(0, 0), a2, voffA);
;             PG8_WAIT_V(8); PG8_WAIT_L(0); PG8_BAR; PG8_MMA(1, 0, At, B0); PG8_MMA(1, 1, At, B1); PG8_BAR; PG8_SCHED;
;             PG8_LDB(B0, 1, 0); PG8_LDB(B1, 1, 1); PG8_SCHED; PG8_LDA(At, 1, 0); PG8_STAGE(PG8_SA(0, 1), a2 + hstepA, voffA);
;             PG8_WAIT_V(8); PG8_WAIT_L(0); PG8_BAR; PG8_MMA(0, 0, At, B0); PG8_MMA(0, 1, At, B1); PG8_BAR; PG8_SCHED;
;             PG8_LDA(At, 1, 1); PG8_STAGE(PG8_SB(1, 0), b3, voffB); PG8_STAGE(PG8_SB(1, 1), b3 + hstepB, voffB); PG8_STAGE(PG8_SA(1, 0), a3, voffA);
;             PG8_WAIT_V(8); PG8_WAIT_L(0); PG8_BAR; PG8_MMA(1, 0, At, B0); PG8_MMA(1, 1, At, B1); PG8_BAR; PG8_SCHED;
	s_add_i32 s78, s90, s3
	v_lshl_add_u64 v[148:149], v[148:149], 0, s[12:13]
	s_mov_b32 m0, s78
	ds_read_b128 v[190:193], v155 offset:49152
	ds_read_b128 v[194:197], v155 offset:50176
	ds_read_b128 v[198:201], v155 offset:51200
	ds_read_b128 v[202:205], v155 offset:52224
	ds_read_b128 v[206:209], v155 offset:53248
	ds_read_b128 v[210:213], v155 offset:54272
	ds_read_b128 v[214:217], v155 offset:55296
	ds_read_b128 v[218:221], v155 offset:56320
	global_load_lds_dwordx4 v[148:149], off
	s_add_i32 m0, s78, 0x2000
	s_add_u32 s76, s76, 0x40080
	v_lshl_add_u64 v[148:149], v[174:175], 0, s[12:13]
	s_addc_u32 s77, s77, 0
	s_add_i32 s78, s91, s3
	global_load_lds_dwordx4 v[148:149], off
	v_lshl_add_u64 v[148:149], s[76:77], 0, v[130:131]
	s_mov_b32 m0, s78
	s_nop 0
	global_load_lds_dwordx4 v[148:149], off
	v_lshl_add_u64 v[148:149], s[76:77], 0, v[134:135]
	s_add_i32 m0, s78, 0x2000
	s_nop 0
	global_load_lds_dwordx4 v[148:149], off
	v_lshl_add_u64 v[148:149], v[222:223], 0, s[12:13]
	s_mov_b32 m0, s57
	s_nop 0
	global_load_lds_dwordx4 v[148:149], off
	v_lshl_add_u64 v[148:149], v[226:227], 0, s[12:13]
	s_mov_b32 m0, s80
	s_nop 0
	global_load_lds_dwordx4 v[148:149], off
	s_waitcnt vmcnt(8)
	s_waitcnt lgkmcnt(0)
	s_barrier
	s_setprio 1
	s_waitcnt lgkmcnt(0)
	v_mfma_f32_16x16x32_bf16 v[60:63], v[144:147], v[190:193], v[60:63]
	v_mfma_f32_16x16x32_bf16 v[56:59], v[162:165], v[190:193], v[56:59]
	v_mfma_f32_16x16x32_bf16 v[44:47], v[144:147], v[198:201], v[44:47]
	v_mfma_f32_16x16x32_bf16 v[40:43], v[162:165], v[198:201], v[40:43]
	v_mfma_f32_16x16x32_bf16 v[28:31], v[144:147], v[206:209], v[28:31]
	v_mfma_f32_16x16x32_bf16 v[24:27], v[162:165], v[206:209], v[24:27]
	v_mfma_f32_16x16x32_bf16 v[12:15], v[144:147], v[214:217], v[12:15]
	v_mfma_f32_16x16x32_bf16 v[8:11], v[162:165], v[214:217], v[8:11]
	v_mfma_f32_16x16x32_bf16 v[60:63], v[158:161], v[194:197], v[60:63]
	v_mfma_f32_16x16x32_bf16 v[56:59], v[166:169], v[194:197], v[56:59]
	v_mfma_f32_16x16x32_bf16 v[44:47], v[158:161], v[202:205], v[44:47]
	v_mfma_f32_16x16x32_bf16 v[40:43], v[166:169], v[202:205], v[40:43]
	v_mfma_f32_16x16x32_bf16 v[28:31], v[158:161], v[210:213], v[28:31]
	v_mfma_f32_16x16x32_bf16 v[24:27], v[166:169], v[210:213], v[24:27]
	v_mfma_f32_16x16x32_bf16 v[12:15], v[158:161], v[218:221], v[12:15]
	v_mfma_f32_16x16x32_bf16 v[8:11], v[166:169], v[218:221], v[8:11]
	s_setprio 0
	s_setprio 1
	v_mfma_f32_16x16x32_bf16 v[52:55], v[170:173], v[190:193], v[52:55]
	v_mfma_f32_16x16x32_bf16 v[48:51], v[182:185], v[190:193], v[48:51]
	v_mfma_f32_16x16x32_bf16 v[36:39], v[170:173], v[198:201], v[36:39]
	v_mfma_f32_16x16x32_bf16 v[32:35], v[182:185], v[198:201], v[32:35]
	v_mfma_f32_16x16x32_bf16 v[20:23], v[170:173], v[206:209], v[20:23]
	v_mfma_f32_16x16x32_bf16 v[16:19], v[182:185], v[206:209], v[16:19]
	v_mfma_f32_16x16x32_bf16 v[4:7], v[170:173], v[214:217], v[4:7]
	v_mfma_f32_16x16x32_bf16 v[0:3], v[182:185], v[214:217], v[0:3]
	v_mfma_f32_16x16x32_bf16 v[52:55], v[178:181], v[194:197], v[52:55]
	v_mfma_f32_16x16x32_bf16 v[48:51], v[186:189], v[194:197], v[48:51]
	v_mfma_f32_16x16x32_bf16 v[36:39], v[178:181], v[202:205], v[36:39]
	v_mfma_f32_16x16x32_bf16 v[32:35], v[186:189], v[202:205], v[32:35]
	v_mfma_f32_16x16x32_bf16 v[20:23], v[178:181], v[210:213], v[20:23]
	v_mfma_f32_16x16x32_bf16 v[16:19], v[186:189], v[210:213], v[16:19]
	v_mfma_f32_16x16x32_bf16 v[4:7], v[178:181], v[218:221], v[4:7]
	v_mfma_f32_16x16x32_bf16 v[0:3], v[186:189], v[218:221], v[0:3]
	s_setprio 0
	s_barrier
	s_add_i32 s89, s89, 2
	s_add_u32 s74, s74, 0x100
	s_addc_u32 s75, s75, 0
	s_add_u32 s87, s87, 0x100
	s_addc_u32 s88, s88, 0
	s_cmp_gt_u32 s89, 13

; __device__ __forceinline__ f32x4 gelu4(f32x4 v) { const f32x2 a = gelu_pk((f32x2){v[0], v[1]}), b = gelu_pk((f32x2){v[2], v[3]}); return (f32x4){a.x, a.y, b.x, b.y}; }
; #define EPI_IT_ROW(it) EPI_ROW((it) >> 2, (it) & 3)
; #define EPI_LOAD_RR(ssp) float rr[8]; _Pragma("unroll") for (int it = 0; it < 8; ++it) rr[it] = (ssp)[EPI_IT_ROW(it)]; _Pragma("unroll") for (int it = 0; it < 8; ++it) rr[it] = rms_r(rr[it])
; #define EPI_PACK8(v0, v1) (u32x4){pk2((v0)[0], (v0)[1]), pk2((v0)[2], (v0)[3]), pk2((v1)[0], (v1)[1]), pk2((v1)[2], (v1)[3])}
; __device__ __forceinline__ f32x2 gelu_pk(f32x2 v) {
;     const f32x2 av = __builtin_elementwise_abs(v), d = av * 0.2316418882f + 1.0f;
;     f32x2 t; t.x = __builtin_amdgcn_rcpf(d.x); t.y = __builtin_amdgcn_rcpf(d.y);
;     f32x2 q = t * 0.5307027145f + (-0.7265760135f); q = q * t + 0.7107068705f; q = q * t + (-0.142248368f); q = q * t + 0.127414796f; q = q * t;
;     const f32x2 s = (v * v) * (-0.72134752044f);
;     f32x2 e; e.x = __builtin_amdgcn_exp2f(s.x); e.y = __builtin_amdgcn_exp2f(s.y);
;     const f32x2 m = v * (q * e), r = v - m;
;     f32x2 o; o.x = v.x < 0.f ? m.x : r.x; o.y = v.y < 0.f ? m.y : r.y; return o;
;     __device__ __forceinline__ void operator()(AccRef acc, const Unit& u, int wr, int wc, int fr, int fq) const {
;         asm volatile("" : "+v"(fr), "+v"(fq));
;         const bool act = u.pn < 4;
;         EPI_LOAD_RR(ss);
; #pragma unroll
;         for (int it = 0; it < 8; ++it) { const int ai = it >> 2, m = it & 3, row = EPI_IT_ROW(it);
; #pragma unroll
;             for (int bj = 0; bj < 2; ++bj) { f32x4 v0 = acc[ai][bj][m][0] * rr[it], v1 = acc[ai][bj][m][1] * rr[it];
;                 if (act) { v0 = gelu4(v0); v1 = gelu4(v1); }
;                 *(u32x4*)(O + (size_t)row * AB_IN + EPI_COL(bj)) = EPI_PACK8(v0, v1); } }
.LBB0_195:
	v_mov_b32_e32 v144, v150
	v_mov_b32_e32 v163, v151
	s_lshl_b32 s7, s72, 8
	s_add_i32 s7, s7, s41
	v_add_u32_e32 v144, s7, v144
	v_ashrrev_i32_e32 v145, 31, v144
	v_lshl_add_u64 v[146:147], v[144:145], 2, s[50:51]
	v_mov_b32_e32 v148, v240
	v_mov_b32_e32 v162, v241
	v_mov_b32_e32 v161, v242
	v_mov_b32_e32 v160, v243
	v_mov_b32_e32 v159, v244
	v_mov_b32_e32 v158, v245
	v_mov_b32_e32 v157, v246
	v_mov_b32_e32 v145, v247
	s_cmp_lt_i32 s6, 4
	s_cselect_b64 s[72:73], -1, 0
	s_cmp_gt_i32 s6, 3
	s_nop 0
	v_fmamk_f32 v146, v148, 0x3a800000, v156
	v_rsq_f32_e32 v146, v146
	s_nop 0
	v_pk_mul_f32 v[126:127], v[126:127], v[146:147] op_sel_hi:[1,0]
	v_pk_mul_f32 v[124:125], v[124:125], v[146:147] op_sel_hi:[1,0]
	v_pk_mul_f32 v[122:123], v[122:123], v[146:147] op_sel_hi:[1,0]
	v_pk_mul_f32 v[148:149], v[120:121], v[146:147] op_sel_hi:[1,0]
	s_cbranch_scc1 .LBB0_197
	v_and_b32_e32 v121, 0x7fffffff, v125
	v_and_b32_e32 v120, 0x7fffffff, v124
	v_pk_fma_f32 v[120:121], v[120:121], s[18:19], 1.0 op_sel_hi:[1,0,0]
	v_mov_b64_e32 v[164:165], s[34:35]
	v_rcp_f32_e32 v120, v120
	v_rcp_f32_e32 v121, v121
	v_pk_mul_f32 v[168:169], v[124:125], v[124:125]
	v_and_b32_e32 v171, 0x7fffffff, v127
	v_pk_mul_f32 v[168:169], v[168:169], s[56:57] op_sel_hi:[1,0]
	v_pk_fma_f32 v[166:167], v[120:121], s[22:23], v[164:165] op_sel_hi:[1,0,0]
	v_exp_f32_e32 v168, v168
	v_pk_fma_f32 v[166:167], v[120:121], v[166:167], s[38:39] op_sel_hi:[1,1,0]
	v_exp_f32_e32 v169, v169
	v_pk_fma_f32 v[166:167], v[120:121], v[166:167], s[40:41] op_sel_hi:[1,1,0]
	v_and_b32_e32 v170, 0x7fffffff, v126
	v_pk_fma_f32 v[166:167], v[120:121], v[166:167], s[42:43] op_sel_hi:[1,1,0]
	v_pk_fma_f32 v[170:171], v[170:171], s[18:19], 1.0 op_sel_hi:[1,0,0]
	v_pk_mul_f32 v[120:121], v[120:121], v[166:167]
	v_rcp_f32_e32 v170, v170
	v_rcp_f32_e32 v171, v171
	v_pk_mul_f32 v[120:121], v[168:169], v[120:121]
	v_cmp_gt_f32_e32 vcc, 0, v124
	v_pk_mul_f32 v[168:169], v[124:125], v[120:121]
	v_pk_fma_f32 v[120:121], v[124:125], v[120:121], v[124:125] neg_lo:[1,0,0] neg_hi:[1,0,0]
	v_pk_mul_f32 v[166:167], v[126:127], v[126:127]
	v_cndmask_b32_e32 v124, v120, v168, vcc
	v_cmp_gt_f32_e32 vcc, 0, v125
	v_pk_mul_f32 v[166:167], v[166:167], s[56:57] op_sel_hi:[1,0]
	v_and_b32_e32 v168, 0x7fffffff, v148
	v_cndmask_b32_e32 v125, v121, v169, vcc
	v_pk_fma_f32 v[120:121], v[170:171], s[22:23], v[164:165] op_sel_hi:[1,0,0]
	v_exp_f32_e32 v166, v166
	v_pk_fma_f32 v[120:121], v[170:171], v[120:121], s[38:39] op_sel_hi:[1,1,0]
	v_exp_f32_e32 v167, v167
	v_pk_fma_f32 v[120:121], v[170:171], v[120:121], s[40:41] op_sel_hi:[1,1,0]
	v_and_b32_e32 v169, 0x7fffffff, v149
	v_pk_fma_f32 v[120:121], v[170:171], v[120:121], s[42:43] op_sel_hi:[1,1,0]
	v_pk_fma_f32 v[168:169], v[168:169], s[18:19], 1.0 op_sel_hi:[1,0,0]
	v_pk_mul_f32 v[120:121], v[170:171], v[120:121]
	v_rcp_f32_e32 v168, v168
	v_pk_mul_f32 v[120:121], v[166:167], v[120:121]
	v_rcp_f32_e32 v169, v169
	v_pk_mul_f32 v[166:167], v[126:127], v[120:121]
	v_pk_fma_f32 v[120:121], v[126:127], v[120:121], v[126:127] neg_lo:[1,0,0] neg_hi:[1,0,0]
	v_cmp_gt_f32_e32 vcc, 0, v126
	v_and_b32_e32 v171, 0x7fffffff, v123
	v_and_b32_e32 v170, 0x7fffffff, v122
	v_cndmask_b32_e32 v126, v120, v166, vcc
	v_cmp_gt_f32_e32 vcc, 0, v127
	v_pk_fma_f32 v[170:171], v[170:171], s[18:19], 1.0 op_sel_hi:[1,0,0]
	s_nop 0
	v_cndmask_b32_e32 v127, v121, v167, vcc
	v_pk_mul_f32 v[166:167], v[148:149], v[148:149]
	v_pk_fma_f32 v[120:121], v[168:169], s[22:23], v[164:165] op_sel_hi:[1,0,0]
	v_pk_mul_f32 v[166:167], v[166:167], s[56:57] op_sel_hi:[1,0]
	v_pk_fma_f32 v[120:121], v[168:169], v[120:121], s[38:39] op_sel_hi:[1,1,0]
	v_exp_f32_e32 v166, v166
	v_exp_f32_e32 v167, v167
	v_pk_fma_f32 v[120:121], v[168:169], v[120:121], s[40:41] op_sel_hi:[1,1,0]
	v_rcp_f32_e32 v170, v170
	v_pk_fma_f32 v[120:121], v[168:169], v[120:121], s[42:43] op_sel_hi:[1,1,0]
	v_rcp_f32_e32 v171, v171
	v_pk_mul_f32 v[120:121], v[168:169], v[120:121]
	v_cmp_gt_f32_e32 vcc, 0, v148
	v_pk_mul_f32 v[120:121], v[166:167], v[120:121]
	v_pk_mul_f32 v[168:169], v[122:123], v[122:123]
	v_pk_mul_f32 v[166:167], v[148:149], v[120:121]
	v_pk_fma_f32 v[120:121], v[148:149], v[120:121], v[148:149] neg_lo:[1,0,0] neg_hi:[1,0,0]
	s_nop 0
	v_cndmask_b32_e32 v148, v120, v166, vcc
	v_cmp_gt_f32_e32 vcc, 0, v149
	s_nop 1
	v_cndmask_b32_e32 v149, v121, v167, vcc
	v_pk_fma_f32 v[120:121], v[170:171], s[22:23], v[164:165] op_sel_hi:[1,0,0]
	v_pk_mul_f32 v[164:165], v[168:169], s[56:57] op_sel_hi:[1,0]
	v_pk_fma_f32 v[120:121], v[170:171], v[120:121], s[38:39] op_sel_hi:[1,1,0]
	v_exp_f32_e32 v164, v164
	v_exp_f32_e32 v165, v165
	v_pk_fma_f32 v[120:121], v[170:171], v[120:121], s[40:41] op_sel_hi:[1,1,0]
	v_cmp_gt_f32_e32 vcc, 0, v122
	v_pk_fma_f32 v[120:121], v[170:171], v[120:121], s[42:43] op_sel_hi:[1,1,0]
	s_nop 0
	v_pk_mul_f32 v[120:121], v[170:171], v[120:121]
	s_nop 0
	v_pk_mul_f32 v[120:121], v[164:165], v[120:121]
	s_nop 0
	v_pk_mul_f32 v[164:165], v[122:123], v[120:121]
	v_pk_fma_f32 v[120:121], v[122:123], v[120:121], v[122:123] neg_lo:[1,0,0] neg_hi:[1,0,0]
	s_nop 0
	v_cndmask_b32_e32 v122, v120, v164, vcc
	v_cmp_gt_f32_e32 vcc, 0, v123
	s_nop 1
	v_cndmask_b32_e32 v123, v121, v165, vcc

; #define PG8_STAGE(bufoff, gbase, voff) do { _Pragma("unroll") for (int _i = 0; _i < 2; ++_i) \
;         __builtin_amdgcn_global_load_lds((const unsigned*)((const char*)(gbase) + (voff)[_i]), (LAS unsigned*)(lds + (bufoff) + ldsw + _i * 8192), 16, 0, 0); } while (0)
; #define PG8_LDA(dst, b, h) do { _Pragma("unroll") for (int m = 0; m < 4; ++m) _Pragma("unroll") for (int k = 0; k < 2; ++k) dst[m][k] = *(const LAS bf16x8*)(lds + PG8_SA(b, h) + aoff + m * 2048 + k * 1024); } while (0)
; #define PG8_LDB(dst, b, h) do { _Pragma("unroll") for (int n = 0; n < 2; ++n) _Pragma("unroll") for (int k = 0; k < 2; ++k) dst[n][k] = *(const LAS bf16x8*)(lds + PG8_SB(b, h) + boff + n * 2048 + k * 1024); } while (0)
; #define PG8_MMA(ai, bj, At, Bt) do { __builtin_amdgcn_s_setprio(1); _Pragma("unroll") for (int m = 0; m < 4; ++m) _Pragma("unroll") for (int n = 0; n < 2; ++n) _Pragma("unroll") for (int k = 0; k < 2; ++k) \
;         acc[ai][bj][m][n] = __builtin_amdgcn_mfma_f32_16x16x32_bf16(Bt[n][k], At[m][k], acc[ai][bj][m][n], 0, 0, 0); __builtin_amdgcn_s_setprio(0); } while (0)
; #define PG8_BAR __builtin_amdgcn_s_barrier()
; template <class Epi>
; __device__ __forceinline__ void gemm_phase(LAS unsigned char* lds, const Gemm g, const StaticOrder& S, const Epi& E) {
;     ...
;         const bool has_next = S.next(ui + 1, nxt);
;         const char* nA = has_next ? (const char*)g.A + (size_t)nxt.pm * tstepA : cA; const char* nB = has_next ? (const char*)g.Bt + (size_t)nxt.pn * tstepB : cB;
; #pragma nounroll
;         for (int t = 0; t < nt; t += 2) {
;             const bool last = (t == nt - 2);
;             const char* a1 = cA + (size_t)(t + 1) * kstep;
;             const char* a2 = last ? nA : cA + (size_t)(t + 2) * kstep; const char* b2 = last ? nB : cB + (size_t)(t + 2) * kstep;
;             const char* a3 = a2 + kstep; const char* b3 = b2 + kstep;
;             PG8_LDB(B0, 0, 0); PG8_LDB(B1, 0, 1); PG8_SCHED; PG8_LDA(At, 0, 0); PG8_STAGE(PG8_SA(1, 1), a1 + hstepA, voffA);
;             PG8_WAIT_V(8); PG8_WAIT_L(0); PG8_BAR; PG8_MMA(0, 0, At, B0); PG8_MMA(0, 1, At, B1); PG8_BAR; PG8_SCHED;
;             PG8_LDA(At, 0, 1); PG8_STAGE(PG8_SB(0, 0), b2, voffB); PG8_STAGE(PG8_SB(0, 1), b2 + hstepB, voffB); PG8_STAGE(PG8_SA(0, 0), a2, voffA);
;             PG8_WAIT_V(8); PG8_WAIT_L(0); PG8_BAR; PG8_MMA(1, 0, At, B0); PG8_MMA(1, 1, At, B1); PG8_BAR; PG8_SCHED;
.LBB0_545:
	s_ashr_i32 s71, s70, 31
	s_lshl_b64 s[12:13], s[70:71], 19
	s_add_u32 s72, s24, s12
	s_addc_u32 s73, s25, s13
	s_and_b64 s[12:13], s[4:5], exec
	s_cselect_b32 s1, s73, s9
	s_cselect_b32 s7, s72, s8
	s_ashr_i32 s69, s68, 31
	s_lshl_b64 s[12:13], s[68:69], 19
	s_add_u32 s74, s3, s12
	s_addc_u32 s75, s33, s13
	s_and_b64 s[12:13], s[4:5], exec
	s_cselect_b32 s69, s75, s11
	s_cselect_b32 s71, s74, s10
	s_add_u32 s8, s8, 0x40080
	s_addc_u32 s9, s9, 0
	s_add_u32 s76, s10, 0x100
	s_addc_u32 s77, s11, 0
	s_mov_b32 s89, -2
	s_waitcnt vmcnt(0)
	v_lshl_add_u32 v248, s6, 8, v151
	v_add_u32_e32 v248, s65, v248
	v_ashrrev_i32_e32 v249, 31, v248
	v_lshl_add_u64 v[248:249], v[248:249], 2, s[22:23]
	global_load_dword v240, v[248:249], off
	global_load_dword v241, v[248:249], off offset:64
	global_load_dword v242, v[248:249], off offset:128
	global_load_dword v243, v[248:249], off offset:192
	global_load_dword v244, v[248:249], off offset:512
	global_load_dword v245, v[248:249], off offset:576
	global_load_dword v246, v[248:249], off offset:640
	global_load_dword v247, v[248:249], off offset:704
	ds_read_b128 v[146:149], v162
	ds_read_b128 v[166:169], v162 offset:1024
	ds_read_b128 v[170:173], v162 offset:2048
	ds_read_b128 v[178:181], v162 offset:3072
	ds_read_b128 v[182:185], v163
	ds_read_b128 v[186:189], v163 offset:1024
	ds_read_b128 v[190:193], v163 offset:2048
	ds_read_b128 v[194:197], v163 offset:3072
	s_add_u32 s10, s8, 0xfffc0080
	s_addc_u32 s11, s9, -1
	s_cmp_eq_u32 s89, 12
	s_cselect_b32 s13, s1, s11
	s_cselect_b32 s12, s7, s10
	s_cselect_b32 s11, s69, s77
	s_cselect_b32 s10, s71, s76
	v_lshl_add_u64 v[174:175], s[8:9], 0, v[138:139]
	s_add_i32 m0, s43, 0xc000
	ds_read_b128 v[198:201], v164
	ds_read_b128 v[202:205], v164 offset:1024
	ds_read_b128 v[206:209], v164 offset:2048
	ds_read_b128 v[210:213], v164 offset:3072
	ds_read_b128 v[214:217], v164 offset:4096
	ds_read_b128 v[218:221], v164 offset:5120
	ds_read_b128 v[226:229], v164 offset:6144
	ds_read_b128 v[230:233], v164 offset:7168
	global_load_lds_dwordx4 v[174:175], off
	v_lshl_add_u64 v[174:175], s[8:9], 0, v[140:141]
	s_add_i32 m0, s43, 0xe000
	s_nop 0
	global_load_lds_dwordx4 v[174:175], off
	s_waitcnt vmcnt(8)
	s_waitcnt lgkmcnt(0)
	s_barrier
	s_setprio 1
	s_waitcnt lgkmcnt(0)
	v_mfma_f32_16x16x32_bf16 v[124:127], v[146:149], v[198:201], 0
	v_mfma_f32_16x16x32_bf16 v[120:123], v[170:173], v[198:201], 0
	v_mfma_f32_16x16x32_bf16 v[112:115], v[146:149], v[206:209], 0
	v_mfma_f32_16x16x32_bf16 v[104:107], v[170:173], v[206:209], 0
	v_mfma_f32_16x16x32_bf16 v[100:103], v[146:149], v[214:217], 0
	v_mfma_f32_16x16x32_bf16 v[92:95], v[170:173], v[214:217], 0
	v_mfma_f32_16x16x32_bf16 v[84:87], v[146:149], v[226:229], 0
	v_mfma_f32_16x16x32_bf16 v[76:79], v[170:173], v[226:229], 0
	v_mfma_f32_16x16x32_bf16 v[124:127], v[166:169], v[202:205], v[124:127]
	v_mfma_f32_16x16x32_bf16 v[120:123], v[178:181], v[202:205], v[120:123]
	v_mfma_f32_16x16x32_bf16 v[112:115], v[166:169], v[210:213], v[112:115]
	v_mfma_f32_16x16x32_bf16 v[104:107], v[178:181], v[210:213], v[104:107]
	v_mfma_f32_16x16x32_bf16 v[100:103], v[166:169], v[218:221], v[100:103]
	v_mfma_f32_16x16x32_bf16 v[92:95], v[178:181], v[218:221], v[92:95]
	v_mfma_f32_16x16x32_bf16 v[84:87], v[166:169], v[230:233], v[84:87]
	v_mfma_f32_16x16x32_bf16 v[76:79], v[178:181], v[230:233], v[76:79]
	s_setprio 0
	s_setprio 1
	v_mfma_f32_16x16x32_bf16 v[116:119], v[182:185], v[198:201], 0
	v_mfma_f32_16x16x32_bf16 v[108:111], v[190:193], v[198:201], 0
	v_mfma_f32_16x16x32_bf16 v[96:99], v[182:185], v[206:209], 0
	v_mfma_f32_16x16x32_bf16 v[88:91], v[190:193], v[206:209], 0
	v_mfma_f32_16x16x32_bf16 v[80:83], v[182:185], v[214:217], 0
	v_mfma_f32_16x16x32_bf16 v[72:75], v[190:193], v[214:217], 0
	v_mfma_f32_16x16x32_bf16 v[68:71], v[182:185], v[226:229], 0
	v_mfma_f32_16x16x32_bf16 v[64:67], v[190:193], v[226:229], 0
	v_mfma_f32_16x16x32_bf16 v[116:119], v[186:189], v[202:205], v[116:119]
	v_mfma_f32_16x16x32_bf16 v[108:111], v[194:197], v[202:205], v[108:111]
	v_mfma_f32_16x16x32_bf16 v[96:99], v[186:189], v[210:213], v[96:99]
	v_mfma_f32_16x16x32_bf16 v[88:91], v[194:197], v[210:213], v[88:91]
	v_mfma_f32_16x16x32_bf16 v[80:83], v[186:189], v[218:221], v[80:83]
	v_mfma_f32_16x16x32_bf16 v[72:75], v[194:197], v[218:221], v[72:75]
	v_mfma_f32_16x16x32_bf16 v[68:71], v[186:189], v[230:233], v[68:71]
	v_mfma_f32_16x16x32_bf16 v[64:67], v[194:197], v[230:233], v[64:67]
	s_setprio 0
	s_barrier
	s_add_i32 s90, s85, s39
	v_lshl_add_u64 v[174:175], s[10:11], 0, v[130:131]
	s_mov_b32 m0, s90
	ds_read_b128 v[198:201], v164 offset:16384
	ds_read_b128 v[202:205], v164 offset:17408
	ds_read_b128 v[206:209], v164 offset:18432
	ds_read_b128 v[210:213], v164 offset:19456
	ds_read_b128 v[214:217], v164 offset:20480
	ds_read_b128 v[218:221], v164 offset:21504
	ds_read_b128 v[226:229], v164 offset:22528
	ds_read_b128 v[230:233], v164 offset:23552
	global_load_lds_dwordx4 v[174:175], off
	s_add_i32 m0, s90, 0x2000
	s_add_u32 s90, s10, 0x40000
	v_lshl_add_u64 v[222:223], s[10:11], 0, v[134:135]
	s_addc_u32 s91, s11, 0
	s_add_i32 s92, s86, s39
	global_load_lds_dwordx4 v[222:223], off
	v_lshl_add_u64 v[234:235], s[90:91], 0, v[130:131]
	s_mov_b32 m0, s92
	v_lshl_add_u64 v[236:237], s[12:13], 0, v[132:133]
	global_load_lds_dwordx4 v[234:235], off
	v_lshl_add_u64 v[234:235], s[90:91], 0, v[134:135]
	s_add_i32 m0, s92, 0x2000
	s_nop 0
	global_load_lds_dwordx4 v[234:235], off
	v_lshl_add_u64 v[234:235], s[12:13], 0, v[128:129]
	s_mov_b32 m0, s43
	s_nop 0
	global_load_lds_dwordx4 v[234:235], off
	s_mov_b32 m0, s53
	s_nop 0
	global_load_lds_dwordx4 v[236:237], off
	s_waitcnt vmcnt(8)
	s_waitcnt lgkmcnt(0)
	s_barrier
; #define PG8_STAGE(bufoff, gbase, voff) do { _Pragma("unroll") for (int _i = 0; _i < 2; ++_i) \
;         __builtin_amdgcn_global_load_lds((const unsigned*)((const char*)(gbase) + (voff)[_i]), (LAS unsigned*)(lds + (bufoff) + ldsw + _i * 8192), 16, 0, 0); } while (0)
; #define PG8_LDA(dst, b, h) do { _Pragma("unroll") for (int m = 0; m < 4; ++m) _Pragma("unroll") for (int k = 0; k < 2; ++k) dst[m][k] = *(const LAS bf16x8*)(lds + PG8_SA(b, h) + aoff + m * 2048 + k * 1024); } while (0)
; #define PG8_LDB(dst, b, h) do { _Pragma("unroll") for (int n = 0; n < 2; ++n) _Pragma("unroll") for (int k = 0; k < 2; ++k) dst[n][k] = *(const LAS bf16x8*)(lds + PG8_SB(b, h) + boff + n * 2048 + k * 1024); } while (0)
; #define PG8_MMA(ai, bj, At, Bt) do { __builtin_amdgcn_s_setprio(1); _Pragma("unroll") for (int m = 0; m < 4; ++m) _Pragma("unroll") for (int n = 0; n < 2; ++n) _Pragma("unroll") for (int k = 0; k < 2; ++k) \
;         acc[ai][bj][m][n] = __builtin_amdgcn_mfma_f32_16x16x32_bf16(Bt[n][k], At[m][k], acc[ai][bj][m][n], 0, 0, 0); __builtin_amdgcn_s_setprio(0); } while (0)
; #define PG8_WAIT_V(n) asm volatile("s_waitcnt vmcnt(" #n ")" ::: "memory")
; #define PG8_WAIT_L(n) asm volatile("s_waitcnt lgkmcnt(" #n ")" ::: "memory")
; #define PG8_BAR __builtin_amdgcn_s_barrier()
; #define PG8_SCHED __builtin_amdgcn_sched_barrier(0)
; template <class Epi>
; __device__ __forceinline__ void gemm_phase(LAS unsigned char* lds, const Gemm g, const StaticOrder& S, const Epi& E) {
;     ...
;             PG8_WAIT_V(8); PG8_WAIT_L(0); PG8_BAR; PG8_MMA(1, 0, At, B0); PG8_MMA(1, 1, At, B1); PG8_BAR; PG8_SCHED;
;             PG8_LDB(B0, 1, 0); PG8_LDB(B1, 1, 1); PG8_SCHED; PG8_LDA(At, 1, 0); PG8_STAGE(PG8_SA(0, 1), a2 + hstepA, voffA);
;             PG8_WAIT_V(8); PG8_WAIT_L(0); PG8_BAR; PG8_MMA(0, 0, At, B0); PG8_MMA(0, 1, At, B1); PG8_BAR; PG8_SCHED;
;             PG8_LDA(At, 1, 1); PG8_STAGE(PG8_SB(1, 0), b3, voffB); PG8_STAGE(PG8_SB(1, 1), b3 + hstepB, voffB); PG8_STAGE(PG8_SA(1, 0), a3, voffA);
	s_setprio 1
	s_waitcnt lgkmcnt(0)
	v_mfma_f32_16x16x32_bf16 v[60:63], v[146:149], v[198:201], 0
	v_mfma_f32_16x16x32_bf16 v[56:59], v[170:173], v[198:201], 0
	v_mfma_f32_16x16x32_bf16 v[52:55], v[146:149], v[206:209], 0
	v_mfma_f32_16x16x32_bf16 v[44:47], v[170:173], v[206:209], 0
	v_mfma_f32_16x16x32_bf16 v[36:39], v[146:149], v[214:217], 0
	v_mfma_f32_16x16x32_bf16 v[28:31], v[170:173], v[214:217], 0
	v_mfma_f32_16x16x32_bf16 v[20:23], v[146:149], v[226:229], 0
	v_mfma_f32_16x16x32_bf16 v[12:15], v[170:173], v[226:229], 0
	v_mfma_f32_16x16x32_bf16 v[60:63], v[166:169], v[202:205], v[60:63]
	v_mfma_f32_16x16x32_bf16 v[56:59], v[178:181], v[202:205], v[56:59]
	v_mfma_f32_16x16x32_bf16 v[52:55], v[166:169], v[210:213], v[52:55]
	v_mfma_f32_16x16x32_bf16 v[44:47], v[178:181], v[210:213], v[44:47]
	v_mfma_f32_16x16x32_bf16 v[36:39], v[166:169], v[218:221], v[36:39]
	v_mfma_f32_16x16x32_bf16 v[28:31], v[178:181], v[218:221], v[28:31]
	v_mfma_f32_16x16x32_bf16 v[20:23], v[166:169], v[230:233], v[20:23]
	v_mfma_f32_16x16x32_bf16 v[12:15], v[178:181], v[230:233], v[12:15]
	s_setprio 0
	s_setprio 1
	v_mfma_f32_16x16x32_bf16 v[48:51], v[182:185], v[198:201], 0
	v_mfma_f32_16x16x32_bf16 v[40:43], v[190:193], v[198:201], 0
	v_mfma_f32_16x16x32_bf16 v[32:35], v[182:185], v[206:209], 0
	v_mfma_f32_16x16x32_bf16 v[24:27], v[190:193], v[206:209], 0
	v_mfma_f32_16x16x32_bf16 v[16:19], v[182:185], v[214:217], 0
	v_mfma_f32_16x16x32_bf16 v[8:11], v[190:193], v[214:217], 0
	v_mfma_f32_16x16x32_bf16 v[4:7], v[182:185], v[226:229], 0
	v_mfma_f32_16x16x32_bf16 v[0:3], v[190:193], v[226:229], 0
	v_mfma_f32_16x16x32_bf16 v[48:51], v[186:189], v[202:205], v[48:51]
	v_mfma_f32_16x16x32_bf16 v[40:43], v[194:197], v[202:205], v[40:43]
	v_mfma_f32_16x16x32_bf16 v[32:35], v[186:189], v[210:213], v[32:35]
	v_mfma_f32_16x16x32_bf16 v[24:27], v[194:197], v[210:213], v[24:27]
	v_mfma_f32_16x16x32_bf16 v[16:19], v[186:189], v[218:221], v[16:19]
	v_mfma_f32_16x16x32_bf16 v[8:11], v[194:197], v[218:221], v[8:11]
	v_mfma_f32_16x16x32_bf16 v[4:7], v[186:189], v[230:233], v[4:7]
	v_mfma_f32_16x16x32_bf16 v[0:3], v[194:197], v[230:233], v[0:3]
	s_setprio 0
	s_barrier
	s_add_i32 s90, 0, 0x18000
	v_add_u32_e32 v136, s90, v161
	s_add_i32 s91, 0, 0x1c000
	ds_read_b128 v[146:149], v136
	ds_read_b128 v[166:169], v136 offset:1024
	ds_read_b128 v[170:173], v136 offset:2048
	ds_read_b128 v[178:181], v136 offset:3072
	v_add_u32_e32 v136, s91, v161
	ds_read_b128 v[182:185], v136
	ds_read_b128 v[186:189], v136 offset:1024
	ds_read_b128 v[190:193], v136 offset:2048
	ds_read_b128 v[194:197], v136 offset:3072
	s_add_u32 s12, s12, 0x40000
	s_addc_u32 s13, s13, 0
	s_mov_b32 m0, s55
	v_lshl_add_u64 v[238:239], s[12:13], 0, v[128:129]
	ds_read_b128 v[198:201], v164 offset:32768
	ds_read_b128 v[202:205], v164 offset:33792
	ds_read_b128 v[206:209], v164 offset:34816
	ds_read_b128 v[210:213], v164 offset:35840
	ds_read_b128 v[214:217], v164 offset:36864
	ds_read_b128 v[218:221], v164 offset:37888
	ds_read_b128 v[226:229], v164 offset:38912
	ds_read_b128 v[230:233], v164 offset:39936
	global_load_lds_dwordx4 v[238:239], off
	v_lshl_add_u64 v[238:239], s[12:13], 0, v[132:133]
	s_mov_b32 m0, s57
	s_nop 0
	global_load_lds_dwordx4 v[238:239], off
	s_waitcnt vmcnt(8)
	s_waitcnt lgkmcnt(0)
	s_barrier
	s_setprio 1
	s_waitcnt lgkmcnt(0)
	v_mfma_f32_16x16x32_bf16 v[124:127], v[146:149], v[198:201], v[124:127]
	v_mfma_f32_16x16x32_bf16 v[120:123], v[170:173], v[198:201], v[120:123]
	v_mfma_f32_16x16x32_bf16 v[112:115], v[146:149], v[206:209], v[112:115]
	v_mfma_f32_16x16x32_bf16 v[104:107], v[170:173], v[206:209], v[104:107]
	v_mfma_f32_16x16x32_bf16 v[100:103], v[146:149], v[214:217], v[100:103]
	v_mfma_f32_16x16x32_bf16 v[92:95], v[170:173], v[214:217], v[92:95]
	v_mfma_f32_16x16x32_bf16 v[84:87], v[146:149], v[226:229], v[84:87]
	v_mfma_f32_16x16x32_bf16 v[76:79], v[170:173], v[226:229], v[76:79]
	v_mfma_f32_16x16x32_bf16 v[124:127], v[166:169], v[202:205], v[124:127]
	v_mfma_f32_16x16x32_bf16 v[120:123], v[178:181], v[202:205], v[120:123]
	v_mfma_f32_16x16x32_bf16 v[112:115], v[166:169], v[210:213], v[112:115]
	v_mfma_f32_16x16x32_bf16 v[104:107], v[178:181], v[210:213], v[104:107]
	v_mfma_f32_16x16x32_bf16 v[100:103], v[166:169], v[218:221], v[100:103]
	v_mfma_f32_16x16x32_bf16 v[92:95], v[178:181], v[218:221], v[92:95]
	v_mfma_f32_16x16x32_bf16 v[84:87], v[166:169], v[230:233], v[84:87]
	v_mfma_f32_16x16x32_bf16 v[76:79], v[178:181], v[230:233], v[76:79]
	s_setprio 0
	s_setprio 1
	v_mfma_f32_16x16x32_bf16 v[116:119], v[182:185], v[198:201], v[116:119]
	v_mfma_f32_16x16x32_bf16 v[108:111], v[190:193], v[198:201], v[108:111]
	v_mfma_f32_16x16x32_bf16 v[96:99], v[182:185], v[206:209], v[96:99]
	v_mfma_f32_16x16x32_bf16 v[88:91], v[190:193], v[206:209], v[88:91]
	v_mfma_f32_16x16x32_bf16 v[80:83], v[182:185], v[214:217], v[80:83]
	v_mfma_f32_16x16x32_bf16 v[72:75], v[190:193], v[214:217], v[72:75]
	v_mfma_f32_16x16x32_bf16 v[68:71], v[182:185], v[226:229], v[68:71]
	v_mfma_f32_16x16x32_bf16 v[64:67], v[190:193], v[226:229], v[64:67]
	v_mfma_f32_16x16x32_bf16 v[116:119], v[186:189], v[202:205], v[116:119]
	v_mfma_f32_16x16x32_bf16 v[108:111], v[194:197], v[202:205], v[108:111]
	v_mfma_f32_16x16x32_bf16 v[96:99], v[186:189], v[210:213], v[96:99]
	v_mfma_f32_16x16x32_bf16 v[88:91], v[194:197], v[210:213], v[88:91]
	v_mfma_f32_16x16x32_bf16 v[80:83], v[186:189], v[218:221], v[80:83]
	v_mfma_f32_16x16x32_bf16 v[72:75], v[194:197], v[218:221], v[72:75]
	v_mfma_f32_16x16x32_bf16 v[68:71], v[186:189], v[230:233], v[68:71]
	v_mfma_f32_16x16x32_bf16 v[64:67], v[194:197], v[230:233], v[64:67]
	s_setprio 0
	s_barrier
; #define PG8_STAGE(bufoff, gbase, voff) do { _Pragma("unroll") for (int _i = 0; _i < 2; ++_i) \
;         __builtin_amdgcn_global_load_lds((const unsigned*)((const char*)(gbase) + (voff)[_i]), (LAS unsigned*)(lds + (bufoff) + ldsw + _i * 8192), 16, 0, 0); } while (0)
; #define PG8_LDA(dst, b, h) do { _Pragma("unroll") for (int m = 0; m < 4; ++m) _Pragma("unroll") for (int k = 0; k < 2; ++k) dst[m][k] = *(const LAS bf16x8*)(lds + PG8_SA(b, h) + aoff + m * 2048 + k * 1024); } while (0)
; #define PG8_LDB(dst, b, h) do { _Pragma("unroll") for (int n = 0; n < 2; ++n) _Pragma("unroll") for (int k = 0; k < 2; ++k) dst[n][k] = *(const LAS bf16x8*)(lds + PG8_SB(b, h) + boff + n * 2048 + k * 1024); } while (0)
; #define PG8_WAIT_V(n) asm volatile("s_waitcnt vmcnt(" #n ")" ::: "memory")
; #define PG8_WAIT_L(n) asm volatile("s_waitcnt lgkmcnt(" #n ")" ::: "memory")
; template <class Epi>
; __device__ __forceinline__ void gemm_phase(LAS unsigned char* lds, const Gemm g, const StaticOrder& S, const Epi& E) {
;     ...
;         for (int t = 0; t < nt; t += 2) {
;             const bool last = (t == nt - 2);
;             const char* a1 = cA + (size_t)(t + 1) * kstep;
;             const char* a2 = last ? nA : cA + (size_t)(t + 2) * kstep; const char* b2 = last ? nB : cB + (size_t)(t + 2) * kstep;
;             const char* a3 = a2 + kstep; const char* b3 = b2 + kstep;
;             PG8_LDB(B0, 0, 0); PG8_LDB(B1, 0, 1); PG8_SCHED; PG8_LDA(At, 0, 0); PG8_STAGE(PG8_SA(1, 1), a1 + hstepA, voffA);
;             PG8_WAIT_V(8); PG8_WAIT_L(0); PG8_BAR; PG8_MMA(0, 0, At, B0); PG8_MMA(0, 1, At, B1); PG8_BAR; PG8_SCHED;
;             PG8_LDA(At, 0, 1); PG8_STAGE(PG8_SB(0, 0), b2, voffB); PG8_STAGE(PG8_SB(0, 1), b2 + hstepB, voffB); PG8_STAGE(PG8_SA(0, 0), a2, voffA);
;             PG8_WAIT_V(8); PG8_WAIT_L(0); PG8_BAR; PG8_MMA(1, 0, At, B0); PG8_MMA(1, 1, At, B1); PG8_BAR; PG8_SCHED;
;             PG8_LDB(B0, 1, 0); PG8_LDB(B1, 1, 1); PG8_SCHED; PG8_LDA(At, 1, 0); PG8_STAGE(PG8_SA(0, 1), a2 + hstepA, voffA);
;             PG8_WAIT_V(8); PG8_WAIT_L(0); PG8_BAR; PG8_MMA(0, 0, At, B0); PG8_MMA(0, 1, At, B1); PG8_BAR; PG8_SCHED;
;             PG8_LDA(At, 1, 1); PG8_STAGE(PG8_SB(1, 0), b3, voffB); PG8_STAGE(PG8_SB(1, 1), b3 + hstepB, voffB); PG8_STAGE(PG8_SA(1, 0), a3, voffA);
;             PG8_WAIT_V(8); PG8_WAIT_L(0); PG8_BAR; PG8_MMA(1, 0, At, B0); PG8_MMA(1, 1, At, B1); PG8_BAR; PG8_SCHED;
	s_add_i32 s12, s90, s39
	v_lshl_add_u64 v[174:175], v[174:175], 0, s[30:31]
	s_mov_b32 m0, s12
	ds_read_b128 v[198:201], v164 offset:49152
	ds_read_b128 v[202:205], v164 offset:50176
	ds_read_b128 v[206:209], v164 offset:51200
	ds_read_b128 v[210:213], v164 offset:52224
	ds_read_b128 v[214:217], v164 offset:53248
	ds_read_b128 v[218:221], v164 offset:54272
	ds_read_b128 v[226:229], v164 offset:55296
	ds_read_b128 v[230:233], v164 offset:56320
	global_load_lds_dwordx4 v[174:175], off
	s_add_i32 m0, s12, 0x2000
	s_add_u32 s10, s10, 0x40080
	v_lshl_add_u64 v[174:175], v[222:223], 0, s[30:31]
	s_addc_u32 s11, s11, 0
	s_add_i32 s12, s91, s39
	global_load_lds_dwordx4 v[174:175], off
	v_lshl_add_u64 v[174:175], s[10:11], 0, v[130:131]
	s_mov_b32 m0, s12
	s_nop 0
	global_load_lds_dwordx4 v[174:175], off
	v_lshl_add_u64 v[174:175], s[10:11], 0, v[134:135]
	s_add_i32 m0, s12, 0x2000
	s_nop 0
	global_load_lds_dwordx4 v[174:175], off
	v_lshl_add_u64 v[174:175], v[234:235], 0, s[30:31]
	s_mov_b32 m0, s79
	s_nop 0
	global_load_lds_dwordx4 v[174:175], off
	v_lshl_add_u64 v[174:175], v[236:237], 0, s[30:31]
	s_mov_b32 m0, s80
	s_nop 0
	global_load_lds_dwordx4 v[174:175], off
	s_waitcnt vmcnt(8)
	s_waitcnt lgkmcnt(0)
	s_barrier
	s_setprio 1
	s_waitcnt lgkmcnt(0)
	v_mfma_f32_16x16x32_bf16 v[60:63], v[146:149], v[198:201], v[60:63]
	v_mfma_f32_16x16x32_bf16 v[56:59], v[170:173], v[198:201], v[56:59]
	v_mfma_f32_16x16x32_bf16 v[52:55], v[146:149], v[206:209], v[52:55]
	v_mfma_f32_16x16x32_bf16 v[44:47], v[170:173], v[206:209], v[44:47]
	v_mfma_f32_16x16x32_bf16 v[36:39], v[146:149], v[214:217], v[36:39]
	v_mfma_f32_16x16x32_bf16 v[28:31], v[170:173], v[214:217], v[28:31]
	v_mfma_f32_16x16x32_bf16 v[20:23], v[146:149], v[226:229], v[20:23]
	v_mfma_f32_16x16x32_bf16 v[12:15], v[170:173], v[226:229], v[12:15]
	v_mfma_f32_16x16x32_bf16 v[60:63], v[166:169], v[202:205], v[60:63]
	v_mfma_f32_16x16x32_bf16 v[56:59], v[178:181], v[202:205], v[56:59]
	v_mfma_f32_16x16x32_bf16 v[52:55], v[166:169], v[210:213], v[52:55]
	v_mfma_f32_16x16x32_bf16 v[44:47], v[178:181], v[210:213], v[44:47]
	v_mfma_f32_16x16x32_bf16 v[36:39], v[166:169], v[218:221], v[36:39]
	v_mfma_f32_16x16x32_bf16 v[28:31], v[178:181], v[218:221], v[28:31]
	v_mfma_f32_16x16x32_bf16 v[20:23], v[166:169], v[230:233], v[20:23]
	v_mfma_f32_16x16x32_bf16 v[12:15], v[178:181], v[230:233], v[12:15]
	s_setprio 0
	s_setprio 1
	v_mfma_f32_16x16x32_bf16 v[48:51], v[182:185], v[198:201], v[48:51]
	v_mfma_f32_16x16x32_bf16 v[40:43], v[190:193], v[198:201], v[40:43]
	v_mfma_f32_16x16x32_bf16 v[32:35], v[182:185], v[206:209], v[32:35]
	v_mfma_f32_16x16x32_bf16 v[24:27], v[190:193], v[206:209], v[24:27]
	v_mfma_f32_16x16x32_bf16 v[16:19], v[182:185], v[214:217], v[16:19]
	v_mfma_f32_16x16x32_bf16 v[8:11], v[190:193], v[214:217], v[8:11]
	v_mfma_f32_16x16x32_bf16 v[4:7], v[182:185], v[226:229], v[4:7]
	v_mfma_f32_16x16x32_bf16 v[0:3], v[190:193], v[226:229], v[0:3]
	v_mfma_f32_16x16x32_bf16 v[48:51], v[186:189], v[202:205], v[48:51]
	v_mfma_f32_16x16x32_bf16 v[40:43], v[194:197], v[202:205], v[40:43]
	v_mfma_f32_16x16x32_bf16 v[32:35], v[186:189], v[210:213], v[32:35]
	v_mfma_f32_16x16x32_bf16 v[24:27], v[194:197], v[210:213], v[24:27]
	v_mfma_f32_16x16x32_bf16 v[16:19], v[186:189], v[218:221], v[16:19]
	v_mfma_f32_16x16x32_bf16 v[8:11], v[194:197], v[218:221], v[8:11]
	v_mfma_f32_16x16x32_bf16 v[4:7], v[186:189], v[230:233], v[4:7]
	v_mfma_f32_16x16x32_bf16 v[0:3], v[194:197], v[230:233], v[0:3]
	s_setprio 0
	s_barrier
	s_add_i32 s89, s89, 2
	s_add_u32 s8, s8, 0x100
	s_addc_u32 s9, s9, 0
	s_add_u32 s76, s76, 0x100
	s_addc_u32 s77, s77, 0
	s_cmp_gt_u32 s89, 13

; __device__ __forceinline__ u32x2 pack4(f32x4 v) { return (u32x2){pk2(v[0], v[1]), pk2(v[2], v[3])}; }
; #define EPI_LOAD_RR(ssp) float rr[8]; _Pragma("unroll") for (int it = 0; it < 8; ++it) rr[it] = (ssp)[EPI_IT_ROW(it)]; _Pragma("unroll") for (int it = 0; it < 8; ++it) rr[it] = rms_r(rr[it])
;     __device__ __forceinline__ void operator()(AccRef acc, const Unit& u, int wr, int wc, int fr, int fq) const {
;         asm volatile("" : "+v"(fr), "+v"(fq));
;         const int j0 = u.pn * 128 + wc * 32 + 8 * fq;
;         u32x2 pa[2][2][4][2];
;         { EPI_LOAD_RR(ss);
; #pragma unroll
;           for (int it = 0; it < 8; ++it)
; #pragma unroll
;               for (int bj = 0; bj < 2; ++bj)
; #pragma unroll
;                   for (int n = 0; n < 2; ++n) pa[it >> 2][bj][it & 3][n] = pack4(acc[it >> 2][bj][it & 3][n] * rr[it]); }
.LBB0_549:
	s_lshl_b32 s69, s6, 8
	v_mov_b32_e32 v166, v151
	v_mov_b32_e32 v185, v153
	s_add_i32 s69, s69, s65
	s_lshl_b32 s0, s0, 7
	v_add_u32_e32 v146, s69, v166
	v_ashrrev_i32_e32 v147, 31, v146
	v_lshl_add_u64 v[148:149], v[146:147], 2, s[22:23]
	v_mov_b32_e32 v136, v240
	v_add_u32_e32 v148, 16, v146
	v_add_u32_e32 v170, 32, v146
	v_ashrrev_i32_e32 v149, 31, v148
	v_ashrrev_i32_e32 v171, 31, v170
	v_add_u32_e32 v172, 48, v146
	v_add_u32_e32 v174, 0x80, v146
	v_add_u32_e32 v178, 0x90, v146
	v_add_u32_e32 v180, 0xa0, v146
	v_add_u32_e32 v182, 0xb0, v146
	v_lshl_add_u64 v[168:169], v[148:149], 2, s[22:23]
	v_lshl_add_u64 v[170:171], v[170:171], 2, s[22:23]
	v_ashrrev_i32_e32 v173, 31, v172
	v_ashrrev_i32_e32 v175, 31, v174
	v_ashrrev_i32_e32 v179, 31, v178
	v_ashrrev_i32_e32 v181, 31, v180
	v_ashrrev_i32_e32 v183, 31, v182
	v_lshl_add_u64 v[172:173], v[172:173], 2, s[22:23]
	v_lshl_add_u64 v[174:175], v[174:175], 2, s[22:23]
	v_lshl_add_u64 v[178:179], v[178:179], 2, s[22:23]
	v_lshl_add_u64 v[180:181], v[180:181], 2, s[22:23]
	v_lshl_add_u64 v[182:183], v[182:183], 2, s[22:23]
	v_mov_b32_e32 v147, v241
	v_mov_b32_e32 v149, v242
	v_mov_b32_e32 v150, v243
	v_mov_b32_e32 v152, v244
	v_mov_b32_e32 v167, v245
	s_nop 0
	v_mov_b32_e32 v169, v246
	v_mov_b32_e32 v170, v247
	s_or_b32 s0, s0, s78
	s_nop 0
	v_fmamk_f32 v136, v136, 0x3a800000, v165
	v_rsq_f32_e32 v168, v136
	v_fmamk_f32 v136, v147, 0x3a800000, v165
	v_fmamk_f32 v147, v149, 0x3a800000, v165
	v_fmamk_f32 v149, v150, 0x3a800000, v165
	v_fmamk_f32 v150, v152, 0x3a800000, v165
	v_fmamk_f32 v152, v167, 0x3a800000, v165
	v_fmamk_f32 v167, v169, 0x3a800000, v165
	v_rsq_f32_e32 v172, v136
	v_fmamk_f32 v169, v170, 0x3a800000, v165
	v_rsq_f32_e32 v180, v147
	v_rsq_f32_e32 v184, v150
	v_rsq_f32_e32 v150, v167
	v_rsq_f32_e32 v182, v149
	v_rsq_f32_e32 v152, v152
	v_rsq_f32_e32 v136, v169
	v_pk_mul_f32 v[90:91], v[90:91], v[172:173] op_sel_hi:[1,0]
	v_pk_mul_f32 v[88:89], v[88:89], v[172:173] op_sel_hi:[1,0]
	v_pk_mul_f32 v[110:111], v[110:111], v[168:169] op_sel_hi:[1,0]
	v_pk_mul_f32 v[108:109], v[108:109], v[168:169] op_sel_hi:[1,0]
	v_pk_mul_f32 v[104:105], v[104:105], v[172:173] op_sel_hi:[1,0]
	v_pk_mul_f32 v[100:101], v[100:101], v[180:181] op_sel_hi:[1,0]
	v_cvt_pk_bf16_f32 v89, v88, v89
	v_cvt_pk_bf16_f32 v88, v90, v91
	v_pk_mul_f32 v[90:91], v[82:83], v[180:181] op_sel_hi:[1,0]
	v_pk_mul_f32 v[72:73], v[72:73], v[180:181] op_sel_hi:[1,0]
	v_pk_mul_f32 v[42:43], v[42:43], v[184:185] op_sel_hi:[1,0]
	v_pk_mul_f32 v[10:11], v[10:11], v[150:151] op_sel_hi:[1,0]
	v_pk_mul_f32 v[8:9], v[8:9], v[150:151] op_sel_hi:[1,0]
	v_cvt_pk_bf16_f32 v170, v108, v109
	v_cvt_pk_bf16_f32 v171, v110, v111
	v_pk_mul_f32 v[108:109], v[114:115], v[172:173] op_sel_hi:[1,0]
	v_pk_mul_f32 v[110:111], v[112:113], v[172:173] op_sel_hi:[1,0]
	v_pk_mul_f32 v[106:107], v[106:107], v[172:173] op_sel_hi:[1,0]
	v_pk_mul_f32 v[98:99], v[98:99], v[172:173] op_sel_hi:[1,0]
	v_pk_mul_f32 v[96:97], v[96:97], v[172:173] op_sel_hi:[1,0]
	v_pk_mul_f32 v[102:103], v[102:103], v[180:181] op_sel_hi:[1,0]
	v_cvt_pk_bf16_f32 v167, v104, v105
	v_cvt_pk_bf16_f32 v173, v100, v101
	v_pk_mul_f32 v[80:81], v[80:81], v[180:181] op_sel_hi:[1,0]
	v_cvt_pk_bf16_f32 v83, v90, v91
	v_pk_mul_f32 v[74:75], v[74:75], v[180:181] op_sel_hi:[1,0]
	v_cvt_pk_bf16_f32 v90, v72, v73
	v_pk_mul_f32 v[72:73], v[86:87], v[182:183] op_sel_hi:[1,0]
	v_pk_mul_f32 v[40:41], v[40:41], v[184:185] op_sel_hi:[1,0]
	v_cvt_pk_bf16_f32 v101, v42, v43
	v_pk_mul_f32 v[42:43], v[52:53], v[152:153] op_sel_hi:[1,0]
	v_pk_mul_f32 v[26:27], v[26:27], v[152:153] op_sel_hi:[1,0]
	v_pk_mul_f32 v[24:25], v[24:25], v[152:153] op_sel_hi:[1,0]
	v_cvt_pk_bf16_f32 v104, v8, v9
	v_cvt_pk_bf16_f32 v105, v10, v11
	v_pk_mul_f32 v[8:9], v[22:23], v[136:137] op_sel_hi:[1,0]
	v_pk_mul_f32 v[10:11], v[20:21], v[136:137] op_sel_hi:[1,0]
	v_pk_mul_f32 v[126:127], v[126:127], v[168:169] op_sel_hi:[1,0]
	v_pk_mul_f32 v[124:125], v[124:125], v[168:169] op_sel_hi:[1,0]
	v_pk_mul_f32 v[122:123], v[122:123], v[168:169] op_sel_hi:[1,0]
	v_pk_mul_f32 v[120:121], v[120:121], v[168:169] op_sel_hi:[1,0]
	v_pk_mul_f32 v[118:119], v[118:119], v[168:169] op_sel_hi:[1,0]
	v_pk_mul_f32 v[116:117], v[116:117], v[168:169] op_sel_hi:[1,0]
	v_pk_mul_f32 v[94:95], v[94:95], v[180:181] op_sel_hi:[1,0]
	v_pk_mul_f32 v[92:93], v[92:93], v[180:181] op_sel_hi:[1,0]
	v_cvt_pk_bf16_f32 v174, v108, v109
	v_cvt_pk_bf16_f32 v172, v102, v103
	v_cvt_pk_bf16_f32 v82, v80, v81
	v_cvt_pk_bf16_f32 v91, v74, v75
	v_pk_mul_f32 v[74:75], v[84:85], v[182:183] op_sel_hi:[1,0]
	v_cvt_pk_bf16_f32 v81, v72, v73
	v_pk_mul_f32 v[72:73], v[78:79], v[182:183] op_sel_hi:[1,0]
	v_pk_mul_f32 v[58:59], v[58:59], v[184:185] op_sel_hi:[1,0]
	v_pk_mul_f32 v[56:57], v[56:57], v[184:185] op_sel_hi:[1,0]
; __device__ __forceinline__ f32x4 ror1v(f32x4 v) { return (f32x4){dpp_ror1(v[0]), dpp_ror1(v[1]), dpp_ror1(v[2]), dpp_ror1(v[3])}; }
; __device__ __forceinline__ f32x4 ror2v(f32x4 v) { return (f32x4){dpp_ror2(v[0]), dpp_ror2(v[1]), dpp_ror2(v[2]), dpp_ror2(v[3])}; }
; __device__ __forceinline__ u32x2 pack4(f32x4 v) { return (u32x2){pk2(v[0], v[1]), pk2(v[2], v[3])}; }
; __device__ __forceinline__ f32x4 unpack4(u32x2 w) { return (f32x4){bflo(w.x), bfhi(w.x), bflo(w.y), bfhi(w.y)}; }
;     __device__ __forceinline__ void operator()(AccRef acc, const Unit& u, int wr, int wc, int fr, int fq) const {
;     ...
;                   for (int n = 0; n < 2; ++n) pa[it >> 2][bj][it & 3][n] = pack4(acc[it >> 2][bj][it & 3][n] * rr[it]); }
;         __builtin_amdgcn_sched_barrier(0);
; #pragma unroll
;         for (int ai = 0; ai < 2; ++ai) {
;             const int rowg = u.pm * 256 + ai * 128 + wr * 64; const int grp = rowg >> 6;
; #pragma unroll
;             for (int n = 0; n < 2; ++n) { const unsigned jn = (unsigned)(j0 + 4 * n);
;                 f32x4 cu[4];
;                 {
;                     const f32x4 wu0 = *(const f32x4*)(cw + (DFF + jn)), wu1 = *(const f32x4*)(cw + (UPN + DFF + jn)), wu2 = *(const f32x4*)(cw + (2 * UPN + DFF + jn)), bu = *(const f32x4*)(cb + (DFF + jn));
;                     f32x4 pu1 = (f32x4){0.f, 0.f, 0.f, 0.f}, pu2 = pu1;
; #pragma unroll
;                     for (int m = 0; m < 4; ++m) {
;                         const f32x4 au = unpack4(pa[ai][1][m][n]);
;                         const f32x4 ru1 = ror1v(au), ru2 = ror2v(au);
;                         const f32x4 u1 = fr >= 1 ? ru1 : pu1, u2 = fr >= 2 ? ru2 : pu2;
;                         if (m == 0 && fr < 2) *(f32x4*)(edge + (unsigned)((grp * 4 + fr) * UPN + DFF + jn)) = au;
	v_cvt_pk_bf16_f32 v100, v40, v41
	v_pk_mul_f32 v[40:41], v[54:55], v[152:153] op_sel_hi:[1,0]
	v_cvt_pk_bf16_f32 v112, v42, v43
	v_pk_mul_f32 v[42:43], v[44:45], v[152:153] op_sel_hi:[1,0]
	v_cvt_pk_bf16_f32 v102, v24, v25
	v_cvt_pk_bf16_f32 v103, v26, v27
	v_pk_mul_f32 v[24:25], v[38:39], v[150:151] op_sel_hi:[1,0]
	v_pk_mul_f32 v[26:27], v[36:37], v[150:151] op_sel_hi:[1,0]
	v_cvt_pk_bf16_f32 v108, v10, v11
	v_cvt_pk_bf16_f32 v109, v8, v9
	v_pk_mul_f32 v[8:9], v[14:15], v[136:137] op_sel_hi:[1,0]
	v_pk_mul_f32 v[10:11], v[12:13], v[136:137] op_sel_hi:[1,0]
	v_pk_mul_f32 v[6:7], v[6:7], v[136:137] op_sel_hi:[1,0]
	v_pk_mul_f32 v[4:5], v[4:5], v[136:137] op_sel_hi:[1,0]
	v_pk_mul_f32 v[2:3], v[2:3], v[136:137] op_sel_hi:[1,0]
	v_pk_mul_f32 v[0:1], v[0:1], v[136:137] op_sel_hi:[1,0]
	v_lshl_add_u32 v44, v185, 3, s0
	v_cvt_pk_bf16_f32 v190, v124, v125
	v_cvt_pk_bf16_f32 v189, v126, v127
	v_cvt_pk_bf16_f32 v169, v120, v121
	v_cvt_pk_bf16_f32 v168, v122, v123
	v_cvt_pk_bf16_f32 v126, v116, v117
	v_cvt_pk_bf16_f32 v179, v118, v119
	v_cvt_pk_bf16_f32 v175, v110, v111
	v_cvt_pk_bf16_f32 v149, v106, v107
	v_cvt_pk_bf16_f32 v178, v96, v97
	v_cvt_pk_bf16_f32 v177, v98, v99
	v_cvt_pk_bf16_f32 v127, v92, v93
	v_cvt_pk_bf16_f32 v147, v94, v95
	v_cvt_pk_bf16_f32 v80, v74, v75
	v_pk_mul_f32 v[74:75], v[76:77], v[182:183] op_sel_hi:[1,0]
	v_cvt_pk_bf16_f32 v125, v72, v73
	v_pk_mul_f32 v[72:73], v[70:71], v[182:183] op_sel_hi:[1,0]
	v_cvt_pk_bf16_f32 v124, v74, v75
	v_pk_mul_f32 v[68:69], v[68:69], v[182:183] op_sel_hi:[1,0]
	v_cvt_pk_bf16_f32 v71, v72, v73
	v_pk_mul_f32 v[66:67], v[66:67], v[182:183] op_sel_hi:[1,0]
	v_cvt_pk_bf16_f32 v70, v68, v69
	v_pk_mul_f32 v[64:65], v[64:65], v[182:183] op_sel_hi:[1,0]
	v_cvt_pk_bf16_f32 v85, v66, v67
	v_pk_mul_f32 v[62:63], v[62:63], v[184:185] op_sel_hi:[1,0]
	v_cvt_pk_bf16_f32 v84, v64, v65
	v_pk_mul_f32 v[60:61], v[60:61], v[184:185] op_sel_hi:[1,0]
	v_cvt_pk_bf16_f32 v115, v62, v63
	v_cvt_pk_bf16_f32 v98, v56, v57
	v_cvt_pk_bf16_f32 v99, v58, v59
	v_pk_mul_f32 v[50:51], v[50:51], v[184:185] op_sel_hi:[1,0]
	v_cvt_pk_bf16_f32 v114, v60, v61
	v_pk_mul_f32 v[48:49], v[48:49], v[184:185] op_sel_hi:[1,0]
	v_cvt_pk_bf16_f32 v117, v50, v51
	v_cvt_pk_bf16_f32 v113, v40, v41
	v_pk_mul_f32 v[40:41], v[46:47], v[152:153] op_sel_hi:[1,0]
	v_cvt_pk_bf16_f32 v116, v48, v49
	v_cvt_pk_bf16_f32 v96, v42, v43
	v_pk_mul_f32 v[34:35], v[34:35], v[152:153] op_sel_hi:[1,0]
	v_cvt_pk_bf16_f32 v97, v40, v41
	v_pk_mul_f32 v[32:33], v[32:33], v[152:153] op_sel_hi:[1,0]
	v_cvt_pk_bf16_f32 v119, v34, v35
	v_cvt_pk_bf16_f32 v110, v26, v27
	v_cvt_pk_bf16_f32 v111, v24, v25
	v_pk_mul_f32 v[24:25], v[30:31], v[150:151] op_sel_hi:[1,0]
	v_cvt_pk_bf16_f32 v118, v32, v33
	v_pk_mul_f32 v[26:27], v[28:29], v[150:151] op_sel_hi:[1,0]
	v_cvt_pk_bf16_f32 v95, v24, v25
	v_pk_mul_f32 v[18:19], v[18:19], v[150:151] op_sel_hi:[1,0]
	v_cvt_pk_bf16_f32 v94, v26, v27
	v_pk_mul_f32 v[16:17], v[16:17], v[150:151] op_sel_hi:[1,0]
	v_cvt_pk_bf16_f32 v121, v18, v19
	v_cvt_pk_bf16_f32 v92, v10, v11
	v_cvt_pk_bf16_f32 v93, v8, v9
	v_cvt_pk_bf16_f32 v122, v4, v5
	v_cvt_pk_bf16_f32 v123, v6, v7
	s_nop 0
	v_cvt_pk_bf16_f32 v120, v16, v17
	v_cvt_pk_bf16_f32 v106, v0, v1
	v_cvt_pk_bf16_f32 v107, v2, v3
	v_add_u32_e32 v136, 0xb00, v44
	v_lshlrev_b64 v[12:13], 2, v[136:137]
	v_add_u32_e32 v136, 0x2100, v44
	v_lshl_add_u64 v[54:55], v[136:137], 2, s[66:67]
	v_add_u32_e32 v136, 0x3700, v44
	v_lshl_add_u64 v[52:53], s[66:67], 0, v[12:13]
	v_lshl_add_u64 v[56:57], v[136:137], 2, s[66:67]
	v_lshl_add_u64 v[58:59], s[36:37], 0, v[12:13]
	global_load_dwordx4 v[8:11], v[52:53], off
	global_load_dwordx4 v[0:3], v[54:55], off
	global_load_dwordx4 v[4:7], v[56:57], off
	global_load_dwordx4 v[12:15], v[58:59], off
	s_ashr_i32 s6, s69, 4
	v_add_u32_e32 v16, s6, v166
	v_mul_lo_u32 v152, v16, s87
	v_lshlrev_b32_e32 v36, 16, v126
	v_and_b32_e32 v37, 0xffff0000, v126
	v_lshlrev_b32_e32 v38, 16, v179
	v_and_b32_e32 v39, 0xffff0000, v179
	s_nop 1
	v_cmp_lt_i32_e64 s[10:11], 1, v166
	v_cmp_gt_i32_e64 s[12:13], 2, v166
	v_add_u32_e32 v78, 0xb00, v152
	v_mov_b32_dpp v191, v36 row_ror:1 row_mask:0xf bank_mask:0xf
	v_mov_b32_dpp v194, v37 row_ror:1 row_mask:0xf bank_mask:0xf
	v_mov_b32_dpp v192, v38 row_ror:1 row_mask:0xf bank_mask:0xf
	v_mov_b32_dpp v196, v39 row_ror:1 row_mask:0xf bank_mask:0xf
	v_mov_b32_dpp v193, v36 row_ror:2 row_mask:0xf bank_mask:0xf
	v_mov_b32_dpp v197, v37 row_ror:2 row_mask:0xf bank_mask:0xf
	v_mov_b32_dpp v201, v38 row_ror:2 row_mask:0xf bank_mask:0xf
	v_mov_b32_dpp v204, v39 row_ror:2 row_mask:0xf bank_mask:0xf
	s_and_saveexec_b64 s[0:1], s[12:13]
	s_cbranch_execz .LBB0_551
	v_add_u32_e32 v136, v78, v44
	v_lshl_add_u64 v[16:17], v[136:137], 2, s[28:29]
	global_store_dwordx4 v[16:17], v[36:39], off

; #define PG8_STAGE(bufoff, gbase, voff) do { _Pragma("unroll") for (int _i = 0; _i < 2; ++_i) \
;         __builtin_amdgcn_global_load_lds((const unsigned*)((const char*)(gbase) + (voff)[_i]), (LAS unsigned*)(lds + (bufoff) + ldsw + _i * 8192), 16, 0, 0); } while (0)
; #define PG8_LDA(dst, b, h) do { _Pragma("unroll") for (int m = 0; m < 4; ++m) _Pragma("unroll") for (int k = 0; k < 2; ++k) dst[m][k] = *(const LAS bf16x8*)(lds + PG8_SA(b, h) + aoff + m * 2048 + k * 1024); } while (0)
; #define PG8_LDB(dst, b, h) do { _Pragma("unroll") for (int n = 0; n < 2; ++n) _Pragma("unroll") for (int k = 0; k < 2; ++k) dst[n][k] = *(const LAS bf16x8*)(lds + PG8_SB(b, h) + boff + n * 2048 + k * 1024); } while (0)
; #define PG8_MMA(ai, bj, At, Bt) do { __builtin_amdgcn_s_setprio(1); _Pragma("unroll") for (int m = 0; m < 4; ++m) _Pragma("unroll") for (int n = 0; n < 2; ++n) _Pragma("unroll") for (int k = 0; k < 2; ++k) \
;         acc[ai][bj][m][n] = __builtin_amdgcn_mfma_f32_16x16x32_bf16(Bt[n][k], At[m][k], acc[ai][bj][m][n], 0, 0, 0); __builtin_amdgcn_s_setprio(0); } while (0)
; #define PG8_BAR __builtin_amdgcn_s_barrier()
; template <class Epi>
; __device__ __forceinline__ void gemm_phase(LAS unsigned char* lds, const Gemm g, const StaticOrder& S, const Epi& E) {
;     ...
;         const bool has_next = S.next(ui + 1, nxt);
;         const char* nA = has_next ? (const char*)g.A + (size_t)nxt.pm * tstepA : cA; const char* nB = has_next ? (const char*)g.Bt + (size_t)nxt.pn * tstepB : cB;
; #pragma nounroll
;         for (int t = 0; t < nt; t += 2) {
;             const bool last = (t == nt - 2);
;             const char* a1 = cA + (size_t)(t + 1) * kstep;
;             const char* a2 = last ? nA : cA + (size_t)(t + 2) * kstep; const char* b2 = last ? nB : cB + (size_t)(t + 2) * kstep;
;             const char* a3 = a2 + kstep; const char* b3 = b2 + kstep;
;             PG8_LDB(B0, 0, 0); PG8_LDB(B1, 0, 1); PG8_SCHED; PG8_LDA(At, 0, 0); PG8_STAGE(PG8_SA(1, 1), a1 + hstepA, voffA);
;             PG8_WAIT_V(8); PG8_WAIT_L(0); PG8_BAR; PG8_MMA(0, 0, At, B0); PG8_MMA(0, 1, At, B1); PG8_BAR; PG8_SCHED;
;             PG8_LDA(At, 0, 1); PG8_STAGE(PG8_SB(0, 0), b2, voffB); PG8_STAGE(PG8_SB(0, 1), b2 + hstepB, voffB); PG8_STAGE(PG8_SA(0, 0), a2, voffA);
;             PG8_WAIT_V(8); PG8_WAIT_L(0); PG8_BAR; PG8_MMA(1, 0, At, B0); PG8_MMA(1, 1, At, B1); PG8_BAR; PG8_SCHED;
.LBB0_1017:
	s_ashr_i32 s35, s34, 31
	s_lshl_b64 s[38:39], s[34:35], 19
	s_add_u32 s38, s24, s38
	s_addc_u32 s39, s25, s39
	s_and_b64 s[42:43], s[4:5], exec
	s_cselect_b32 s7, s39, s55
	s_cselect_b32 s35, s38, s54
	s_ashr_i32 s23, s22, 31
	s_lshl_b64 s[42:43], s[22:23], 19
	s_add_u32 s42, s33, s42
	s_addc_u32 s43, s64, s43
	s_and_b64 s[62:63], s[4:5], exec
	s_cselect_b32 s23, s43, s57
	s_cselect_b32 s53, s42, s56
	s_add_u32 s54, s54, 0x40080
	s_addc_u32 s55, s55, 0
	s_add_u32 s83, s56, 0x100
	s_waitcnt vmcnt(0)
	s_addc_u32 s84, s57, 0
	s_mov_b32 s85, -2
	v_lshl_add_u32 v248, s6, 8, v227
	v_add_u32_e32 v248, s74, v248
	v_ashrrev_i32_e32 v249, 31, v248
	v_lshl_add_u64 v[248:249], v[248:249], 2, s[10:11]
	global_load_dword v240, v[248:249], off
	global_load_dword v241, v[248:249], off offset:64
	global_load_dword v242, v[248:249], off offset:128
	global_load_dword v243, v[248:249], off offset:192
	global_load_dword v244, v[248:249], off offset:512
	global_load_dword v245, v[248:249], off offset:576
	global_load_dword v246, v[248:249], off offset:640
	global_load_dword v247, v[248:249], off offset:704
	ds_read_b128 v[0:3], v230
	ds_read_b128 v[4:7], v230 offset:1024
	ds_read_b128 v[8:11], v230 offset:2048
	ds_read_b128 v[12:15], v230 offset:3072
	ds_read_b128 v[144:147], v231
	ds_read_b128 v[148:151], v231 offset:1024
	ds_read_b128 v[152:155], v231 offset:2048
	ds_read_b128 v[156:159], v231 offset:3072
	s_add_u32 s56, s54, 0xfffc0080
	s_addc_u32 s57, s55, -1
	s_cmp_eq_u32 s85, 12
	s_cselect_b32 s63, s7, s57
	s_cselect_b32 s62, s35, s56
	s_cselect_b32 s57, s23, s84
	s_cselect_b32 s56, s53, s83
	v_lshl_add_u64 v[212:213], s[54:55], 0, v[188:189]
	s_add_i32 m0, s68, 0xc000
	ds_read_b128 v[160:163], v232
	ds_read_b128 v[164:167], v232 offset:1024
	ds_read_b128 v[168:171], v232 offset:2048
	ds_read_b128 v[172:175], v232 offset:3072
	ds_read_b128 v[196:199], v232 offset:4096
	ds_read_b128 v[200:203], v232 offset:5120
	ds_read_b128 v[204:207], v232 offset:6144
	ds_read_b128 v[208:211], v232 offset:7168
	global_load_lds_dwordx4 v[212:213], off
	v_lshl_add_u64 v[212:213], s[54:55], 0, v[190:191]
	s_add_i32 m0, s68, 0xe000
	s_nop 0
	global_load_lds_dwordx4 v[212:213], off
	s_waitcnt vmcnt(8)
	s_waitcnt lgkmcnt(0)
	s_barrier
	s_setprio 1
	s_waitcnt lgkmcnt(0)
	v_mfma_f32_16x16x32_bf16 v[140:143], v[0:3], v[160:163], 0
	v_mfma_f32_16x16x32_bf16 v[132:135], v[8:11], v[160:163], 0
	v_mfma_f32_16x16x32_bf16 v[124:127], v[0:3], v[168:171], 0
	v_mfma_f32_16x16x32_bf16 v[120:123], v[8:11], v[168:171], 0
	v_mfma_f32_16x16x32_bf16 v[108:111], v[0:3], v[196:199], 0
	v_mfma_f32_16x16x32_bf16 v[104:107], v[8:11], v[196:199], 0
	v_mfma_f32_16x16x32_bf16 v[92:95], v[0:3], v[204:207], 0
	v_mfma_f32_16x16x32_bf16 v[88:91], v[8:11], v[204:207], 0
	v_mfma_f32_16x16x32_bf16 v[140:143], v[4:7], v[164:167], v[140:143]
	v_mfma_f32_16x16x32_bf16 v[132:135], v[12:15], v[164:167], v[132:135]
	v_mfma_f32_16x16x32_bf16 v[124:127], v[4:7], v[172:175], v[124:127]
	v_mfma_f32_16x16x32_bf16 v[120:123], v[12:15], v[172:175], v[120:123]
	v_mfma_f32_16x16x32_bf16 v[108:111], v[4:7], v[200:203], v[108:111]
	v_mfma_f32_16x16x32_bf16 v[104:107], v[12:15], v[200:203], v[104:107]
	v_mfma_f32_16x16x32_bf16 v[92:95], v[4:7], v[208:211], v[92:95]
	v_mfma_f32_16x16x32_bf16 v[88:91], v[12:15], v[208:211], v[88:91]
	s_setprio 0
	s_setprio 1
	v_mfma_f32_16x16x32_bf16 v[136:139], v[144:147], v[160:163], 0
	v_mfma_f32_16x16x32_bf16 v[128:131], v[152:155], v[160:163], 0
	v_mfma_f32_16x16x32_bf16 v[116:119], v[144:147], v[168:171], 0
	v_mfma_f32_16x16x32_bf16 v[112:115], v[152:155], v[168:171], 0
	v_mfma_f32_16x16x32_bf16 v[100:103], v[144:147], v[196:199], 0
	v_mfma_f32_16x16x32_bf16 v[96:99], v[152:155], v[196:199], 0
	v_mfma_f32_16x16x32_bf16 v[84:87], v[144:147], v[204:207], 0
	v_mfma_f32_16x16x32_bf16 v[80:83], v[152:155], v[204:207], 0
	v_mfma_f32_16x16x32_bf16 v[136:139], v[148:151], v[164:167], v[136:139]
	v_mfma_f32_16x16x32_bf16 v[128:131], v[156:159], v[164:167], v[128:131]
	v_mfma_f32_16x16x32_bf16 v[116:119], v[148:151], v[172:175], v[116:119]
	v_mfma_f32_16x16x32_bf16 v[112:115], v[156:159], v[172:175], v[112:115]
	v_mfma_f32_16x16x32_bf16 v[100:103], v[148:151], v[200:203], v[100:103]
	v_mfma_f32_16x16x32_bf16 v[96:99], v[156:159], v[200:203], v[96:99]
	v_mfma_f32_16x16x32_bf16 v[84:87], v[148:151], v[208:211], v[84:87]
	v_mfma_f32_16x16x32_bf16 v[80:83], v[156:159], v[208:211], v[80:83]
	s_setprio 0
	s_barrier
	s_add_i32 s86, s81, s65
	v_lshl_add_u64 v[212:213], s[56:57], 0, v[180:181]
	s_mov_b32 m0, s86
	ds_read_b128 v[160:163], v232 offset:16384
	ds_read_b128 v[164:167], v232 offset:17408
	ds_read_b128 v[168:171], v232 offset:18432
	ds_read_b128 v[172:175], v232 offset:19456
	ds_read_b128 v[196:199], v232 offset:20480
	ds_read_b128 v[200:203], v232 offset:21504
	ds_read_b128 v[204:207], v232 offset:22528
	ds_read_b128 v[208:211], v232 offset:23552
	global_load_lds_dwordx4 v[212:213], off
	s_add_i32 m0, s86, 0x2000
	s_add_u32 s86, s56, 0x40000
	v_lshl_add_u64 v[214:215], s[56:57], 0, v[184:185]
	s_addc_u32 s87, s57, 0
	s_add_i32 s88, s82, s65
	global_load_lds_dwordx4 v[214:215], off
	v_lshl_add_u64 v[216:217], s[86:87], 0, v[180:181]
	s_mov_b32 m0, s88
	v_lshl_add_u64 v[218:219], s[62:63], 0, v[182:183]
	global_load_lds_dwordx4 v[216:217], off
	v_lshl_add_u64 v[216:217], s[86:87], 0, v[184:185]
	s_add_i32 m0, s88, 0x2000
	s_nop 0
	global_load_lds_dwordx4 v[216:217], off
	v_lshl_add_u64 v[216:217], s[62:63], 0, v[178:179]
	s_mov_b32 m0, s68
	s_nop 0
	global_load_lds_dwordx4 v[216:217], off
	s_mov_b32 m0, s69
	s_nop 0
	global_load_lds_dwordx4 v[218:219], off
	s_waitcnt vmcnt(8)
	s_waitcnt lgkmcnt(0)
	s_barrier
; #define PG8_STAGE(bufoff, gbase, voff) do { _Pragma("unroll") for (int _i = 0; _i < 2; ++_i) \
;         __builtin_amdgcn_global_load_lds((const unsigned*)((const char*)(gbase) + (voff)[_i]), (LAS unsigned*)(lds + (bufoff) + ldsw + _i * 8192), 16, 0, 0); } while (0)
; #define PG8_LDA(dst, b, h) do { _Pragma("unroll") for (int m = 0; m < 4; ++m) _Pragma("unroll") for (int k = 0; k < 2; ++k) dst[m][k] = *(const LAS bf16x8*)(lds + PG8_SA(b, h) + aoff + m * 2048 + k * 1024); } while (0)
; #define PG8_LDB(dst, b, h) do { _Pragma("unroll") for (int n = 0; n < 2; ++n) _Pragma("unroll") for (int k = 0; k < 2; ++k) dst[n][k] = *(const LAS bf16x8*)(lds + PG8_SB(b, h) + boff + n * 2048 + k * 1024); } while (0)
; #define PG8_MMA(ai, bj, At, Bt) do { __builtin_amdgcn_s_setprio(1); _Pragma("unroll") for (int m = 0; m < 4; ++m) _Pragma("unroll") for (int n = 0; n < 2; ++n) _Pragma("unroll") for (int k = 0; k < 2; ++k) \
;         acc[ai][bj][m][n] = __builtin_amdgcn_mfma_f32_16x16x32_bf16(Bt[n][k], At[m][k], acc[ai][bj][m][n], 0, 0, 0); __builtin_amdgcn_s_setprio(0); } while (0)
; #define PG8_WAIT_V(n) asm volatile("s_waitcnt vmcnt(" #n ")" ::: "memory")
; #define PG8_WAIT_L(n) asm volatile("s_waitcnt lgkmcnt(" #n ")" ::: "memory")
; #define PG8_BAR __builtin_amdgcn_s_barrier()
; #define PG8_SCHED __builtin_amdgcn_sched_barrier(0)
; template <class Epi>
; __device__ __forceinline__ void gemm_phase(LAS unsigned char* lds, const Gemm g, const StaticOrder& S, const Epi& E) {
;     ...
;             PG8_WAIT_V(8); PG8_WAIT_L(0); PG8_BAR; PG8_MMA(1, 0, At, B0); PG8_MMA(1, 1, At, B1); PG8_BAR; PG8_SCHED;
;             PG8_LDB(B0, 1, 0); PG8_LDB(B1, 1, 1); PG8_SCHED; PG8_LDA(At, 1, 0); PG8_STAGE(PG8_SA(0, 1), a2 + hstepA, voffA);
;             PG8_WAIT_V(8); PG8_WAIT_L(0); PG8_BAR; PG8_MMA(0, 0, At, B0); PG8_MMA(0, 1, At, B1); PG8_BAR; PG8_SCHED;
;             PG8_LDA(At, 1, 1); PG8_STAGE(PG8_SB(1, 0), b3, voffB); PG8_STAGE(PG8_SB(1, 1), b3 + hstepB, voffB); PG8_STAGE(PG8_SA(1, 0), a3, voffA);
	s_setprio 1
	s_waitcnt lgkmcnt(0)
	v_mfma_f32_16x16x32_bf16 v[76:79], v[0:3], v[160:163], 0
	v_mfma_f32_16x16x32_bf16 v[72:75], v[8:11], v[160:163], 0
	v_mfma_f32_16x16x32_bf16 v[60:63], v[0:3], v[168:171], 0
	v_mfma_f32_16x16x32_bf16 v[56:59], v[8:11], v[168:171], 0
	v_mfma_f32_16x16x32_bf16 v[44:47], v[0:3], v[196:199], 0
	v_mfma_f32_16x16x32_bf16 v[40:43], v[8:11], v[196:199], 0
	v_mfma_f32_16x16x32_bf16 v[0:3], v[0:3], v[204:207], 0
	v_mfma_f32_16x16x32_bf16 v[76:79], v[4:7], v[164:167], v[76:79]
	v_mfma_f32_16x16x32_bf16 v[72:75], v[12:15], v[164:167], v[72:75]
	v_mfma_f32_16x16x32_bf16 v[60:63], v[4:7], v[172:175], v[60:63]
	v_mfma_f32_16x16x32_bf16 v[56:59], v[12:15], v[172:175], v[56:59]
	v_mfma_f32_16x16x32_bf16 v[44:47], v[4:7], v[200:203], v[44:47]
	v_mfma_f32_16x16x32_bf16 v[40:43], v[12:15], v[200:203], v[40:43]
	v_mfma_f32_16x16x32_bf16 v[0:3], v[4:7], v[208:211], v[0:3]
	v_mfma_f32_16x16x32_bf16 v[4:7], v[8:11], v[204:207], 0
	v_mfma_f32_16x16x32_bf16 v[4:7], v[12:15], v[208:211], v[4:7]
	s_setprio 0
	s_setprio 1
	v_mfma_f32_16x16x32_bf16 v[20:23], v[144:147], v[168:171], 0
	v_mfma_f32_16x16x32_bf16 v[52:55], v[148:151], v[172:175], v[20:23]
	v_mfma_f32_16x16x32_bf16 v[20:23], v[152:155], v[168:171], 0
	v_mfma_f32_16x16x32_bf16 v[48:51], v[156:159], v[172:175], v[20:23]
	v_mfma_f32_16x16x32_bf16 v[20:23], v[144:147], v[196:199], 0
	v_mfma_f32_16x16x32_bf16 v[36:39], v[148:151], v[200:203], v[20:23]
	v_mfma_f32_16x16x32_bf16 v[20:23], v[152:155], v[196:199], 0
	v_mfma_f32_16x16x32_bf16 v[32:35], v[156:159], v[200:203], v[20:23]
	v_mfma_f32_16x16x32_bf16 v[20:23], v[144:147], v[204:207], 0
	v_mfma_f32_16x16x32_bf16 v[16:19], v[152:155], v[204:207], 0
	v_mfma_f32_16x16x32_bf16 v[8:11], v[144:147], v[160:163], 0
	v_mfma_f32_16x16x32_bf16 v[12:15], v[152:155], v[160:163], 0
	v_mfma_f32_16x16x32_bf16 v[24:27], v[148:151], v[208:211], v[20:23]
	v_mfma_f32_16x16x32_bf16 v[16:19], v[156:159], v[208:211], v[16:19]
	v_mfma_f32_16x16x32_bf16 v[8:11], v[148:151], v[164:167], v[8:11]
	v_mfma_f32_16x16x32_bf16 v[12:15], v[156:159], v[164:167], v[12:15]
	s_setprio 0
	s_barrier
	s_add_i32 s86, 0, 0x18000
	s_add_i32 s87, 0, 0x1c000
	v_add_u32_e32 v68, s86, v229
	v_add_u32_e32 v156, s87, v229
	ds_read_b128 v[20:23], v68
	ds_read_b128 v[28:31], v68 offset:1024
	ds_read_b128 v[64:67], v68 offset:2048
	ds_read_b128 v[68:71], v68 offset:3072
	ds_read_b128 v[144:147], v156
	ds_read_b128 v[148:151], v156 offset:1024
	ds_read_b128 v[152:155], v156 offset:2048
	ds_read_b128 v[156:159], v156 offset:3072
	s_add_u32 s62, s62, 0x40000
	s_addc_u32 s63, s63, 0
	s_mov_b32 m0, s70
	v_lshl_add_u64 v[220:221], s[62:63], 0, v[178:179]
	ds_read_b128 v[160:163], v232 offset:32768
	ds_read_b128 v[164:167], v232 offset:33792
	ds_read_b128 v[168:171], v232 offset:34816
	ds_read_b128 v[172:175], v232 offset:35840
	ds_read_b128 v[196:199], v232 offset:36864
	ds_read_b128 v[200:203], v232 offset:37888
	ds_read_b128 v[204:207], v232 offset:38912
	ds_read_b128 v[208:211], v232 offset:39936
	global_load_lds_dwordx4 v[220:221], off
	v_lshl_add_u64 v[220:221], s[62:63], 0, v[182:183]
	s_mov_b32 m0, s71
	s_nop 0
	global_load_lds_dwordx4 v[220:221], off
	s_waitcnt vmcnt(8)
	s_waitcnt lgkmcnt(0)
	s_barrier
	s_setprio 1
	s_waitcnt lgkmcnt(0)
	v_mfma_f32_16x16x32_bf16 v[140:143], v[20:23], v[160:163], v[140:143]
	v_mfma_f32_16x16x32_bf16 v[132:135], v[64:67], v[160:163], v[132:135]
	v_mfma_f32_16x16x32_bf16 v[124:127], v[20:23], v[168:171], v[124:127]
	v_mfma_f32_16x16x32_bf16 v[120:123], v[64:67], v[168:171], v[120:123]
	v_mfma_f32_16x16x32_bf16 v[108:111], v[20:23], v[196:199], v[108:111]
	v_mfma_f32_16x16x32_bf16 v[104:107], v[64:67], v[196:199], v[104:107]
	v_mfma_f32_16x16x32_bf16 v[92:95], v[20:23], v[204:207], v[92:95]
	v_mfma_f32_16x16x32_bf16 v[88:91], v[64:67], v[204:207], v[88:91]
	v_mfma_f32_16x16x32_bf16 v[140:143], v[28:31], v[164:167], v[140:143]
	v_mfma_f32_16x16x32_bf16 v[132:135], v[68:71], v[164:167], v[132:135]
	v_mfma_f32_16x16x32_bf16 v[124:127], v[28:31], v[172:175], v[124:127]
	v_mfma_f32_16x16x32_bf16 v[120:123], v[68:71], v[172:175], v[120:123]
	v_mfma_f32_16x16x32_bf16 v[108:111], v[28:31], v[200:203], v[108:111]
	v_mfma_f32_16x16x32_bf16 v[104:107], v[68:71], v[200:203], v[104:107]
	v_mfma_f32_16x16x32_bf16 v[92:95], v[28:31], v[208:211], v[92:95]
	v_mfma_f32_16x16x32_bf16 v[88:91], v[68:71], v[208:211], v[88:91]
	s_setprio 0
	s_setprio 1
	v_mfma_f32_16x16x32_bf16 v[136:139], v[144:147], v[160:163], v[136:139]
	v_mfma_f32_16x16x32_bf16 v[128:131], v[152:155], v[160:163], v[128:131]
	v_mfma_f32_16x16x32_bf16 v[116:119], v[144:147], v[168:171], v[116:119]
	v_mfma_f32_16x16x32_bf16 v[112:115], v[152:155], v[168:171], v[112:115]
	v_mfma_f32_16x16x32_bf16 v[100:103], v[144:147], v[196:199], v[100:103]
	v_mfma_f32_16x16x32_bf16 v[96:99], v[152:155], v[196:199], v[96:99]
	v_mfma_f32_16x16x32_bf16 v[84:87], v[144:147], v[204:207], v[84:87]
	v_mfma_f32_16x16x32_bf16 v[80:83], v[152:155], v[204:207], v[80:83]
	v_mfma_f32_16x16x32_bf16 v[136:139], v[148:151], v[164:167], v[136:139]
	v_mfma_f32_16x16x32_bf16 v[128:131], v[156:159], v[164:167], v[128:131]
	v_mfma_f32_16x16x32_bf16 v[116:119], v[148:151], v[172:175], v[116:119]
	v_mfma_f32_16x16x32_bf16 v[112:115], v[156:159], v[172:175], v[112:115]
	v_mfma_f32_16x16x32_bf16 v[100:103], v[148:151], v[200:203], v[100:103]
	v_mfma_f32_16x16x32_bf16 v[96:99], v[156:159], v[200:203], v[96:99]
	v_mfma_f32_16x16x32_bf16 v[84:87], v[148:151], v[208:211], v[84:87]
	v_mfma_f32_16x16x32_bf16 v[80:83], v[156:159], v[208:211], v[80:83]
	s_setprio 0
	s_barrier
; #define PG8_STAGE(bufoff, gbase, voff) do { _Pragma("unroll") for (int _i = 0; _i < 2; ++_i) \
;         __builtin_amdgcn_global_load_lds((const unsigned*)((const char*)(gbase) + (voff)[_i]), (LAS unsigned*)(lds + (bufoff) + ldsw + _i * 8192), 16, 0, 0); } while (0)
; #define PG8_LDA(dst, b, h) do { _Pragma("unroll") for (int m = 0; m < 4; ++m) _Pragma("unroll") for (int k = 0; k < 2; ++k) dst[m][k] = *(const LAS bf16x8*)(lds + PG8_SA(b, h) + aoff + m * 2048 + k * 1024); } while (0)
; #define PG8_LDB(dst, b, h) do { _Pragma("unroll") for (int n = 0; n < 2; ++n) _Pragma("unroll") for (int k = 0; k < 2; ++k) dst[n][k] = *(const LAS bf16x8*)(lds + PG8_SB(b, h) + boff + n * 2048 + k * 1024); } while (0)
; #define PG8_WAIT_V(n) asm volatile("s_waitcnt vmcnt(" #n ")" ::: "memory")
; #define PG8_WAIT_L(n) asm volatile("s_waitcnt lgkmcnt(" #n ")" ::: "memory")
; template <class Epi>
; __device__ __forceinline__ void gemm_phase(LAS unsigned char* lds, const Gemm g, const StaticOrder& S, const Epi& E) {
;     ...
;         for (int t = 0; t < nt; t += 2) {
;             const bool last = (t == nt - 2);
;             const char* a1 = cA + (size_t)(t + 1) * kstep;
;             const char* a2 = last ? nA : cA + (size_t)(t + 2) * kstep; const char* b2 = last ? nB : cB + (size_t)(t + 2) * kstep;
;             const char* a3 = a2 + kstep; const char* b3 = b2 + kstep;
;             PG8_LDB(B0, 0, 0); PG8_LDB(B1, 0, 1); PG8_SCHED; PG8_LDA(At, 0, 0); PG8_STAGE(PG8_SA(1, 1), a1 + hstepA, voffA);
;             PG8_WAIT_V(8); PG8_WAIT_L(0); PG8_BAR; PG8_MMA(0, 0, At, B0); PG8_MMA(0, 1, At, B1); PG8_BAR; PG8_SCHED;
;             PG8_LDA(At, 0, 1); PG8_STAGE(PG8_SB(0, 0), b2, voffB); PG8_STAGE(PG8_SB(0, 1), b2 + hstepB, voffB); PG8_STAGE(PG8_SA(0, 0), a2, voffA);
;             PG8_WAIT_V(8); PG8_WAIT_L(0); PG8_BAR; PG8_MMA(1, 0, At, B0); PG8_MMA(1, 1, At, B1); PG8_BAR; PG8_SCHED;
;             PG8_LDB(B0, 1, 0); PG8_LDB(B1, 1, 1); PG8_SCHED; PG8_LDA(At, 1, 0); PG8_STAGE(PG8_SA(0, 1), a2 + hstepA, voffA);
;             PG8_WAIT_V(8); PG8_WAIT_L(0); PG8_BAR; PG8_MMA(0, 0, At, B0); PG8_MMA(0, 1, At, B1); PG8_BAR; PG8_SCHED;
;             PG8_LDA(At, 1, 1); PG8_STAGE(PG8_SB(1, 0), b3, voffB); PG8_STAGE(PG8_SB(1, 1), b3 + hstepB, voffB); PG8_STAGE(PG8_SA(1, 0), a3, voffA);
;             PG8_WAIT_V(8); PG8_WAIT_L(0); PG8_BAR; PG8_MMA(1, 0, At, B0); PG8_MMA(1, 1, At, B1); PG8_BAR; PG8_SCHED;
	s_add_i32 s62, s86, s65
	v_lshl_add_u64 v[212:213], v[212:213], 0, s[16:17]
	s_mov_b32 m0, s62
	ds_read_b128 v[160:163], v232 offset:49152
	ds_read_b128 v[164:167], v232 offset:50176
	ds_read_b128 v[168:171], v232 offset:51200
	ds_read_b128 v[172:175], v232 offset:52224
	ds_read_b128 v[196:199], v232 offset:53248
	ds_read_b128 v[200:203], v232 offset:54272
	ds_read_b128 v[204:207], v232 offset:55296
	ds_read_b128 v[208:211], v232 offset:56320
	global_load_lds_dwordx4 v[212:213], off
	s_add_i32 m0, s62, 0x2000
	s_add_u32 s56, s56, 0x40080
	v_lshl_add_u64 v[212:213], v[214:215], 0, s[16:17]
	s_addc_u32 s57, s57, 0
	s_add_i32 s62, s87, s65
	global_load_lds_dwordx4 v[212:213], off
	v_lshl_add_u64 v[212:213], s[56:57], 0, v[180:181]
	s_mov_b32 m0, s62
	s_nop 0
	global_load_lds_dwordx4 v[212:213], off
	v_lshl_add_u64 v[212:213], s[56:57], 0, v[184:185]
	s_add_i32 m0, s62, 0x2000
	s_nop 0
	global_load_lds_dwordx4 v[212:213], off
	v_lshl_add_u64 v[212:213], v[216:217], 0, s[16:17]
	s_mov_b32 m0, s76
	s_nop 0
	global_load_lds_dwordx4 v[212:213], off
	v_lshl_add_u64 v[212:213], v[218:219], 0, s[16:17]
	s_mov_b32 m0, s77
	s_nop 0
	global_load_lds_dwordx4 v[212:213], off
	s_waitcnt vmcnt(8)
	s_waitcnt lgkmcnt(0)
	s_barrier
	s_setprio 1
	s_waitcnt lgkmcnt(0)
	v_mfma_f32_16x16x32_bf16 v[76:79], v[20:23], v[160:163], v[76:79]
	v_mfma_f32_16x16x32_bf16 v[60:63], v[20:23], v[168:171], v[60:63]
	v_mfma_f32_16x16x32_bf16 v[44:47], v[20:23], v[196:199], v[44:47]
	v_mfma_f32_16x16x32_bf16 v[0:3], v[20:23], v[204:207], v[0:3]
	v_mfma_f32_16x16x32_bf16 v[76:79], v[28:31], v[164:167], v[76:79]
	v_mfma_f32_16x16x32_bf16 v[72:75], v[64:67], v[160:163], v[72:75]
	v_mfma_f32_16x16x32_bf16 v[60:63], v[28:31], v[172:175], v[60:63]
	v_mfma_f32_16x16x32_bf16 v[56:59], v[64:67], v[168:171], v[56:59]
	v_mfma_f32_16x16x32_bf16 v[44:47], v[28:31], v[200:203], v[44:47]
	v_mfma_f32_16x16x32_bf16 v[40:43], v[64:67], v[196:199], v[40:43]
	v_mfma_f32_16x16x32_bf16 v[28:31], v[28:31], v[208:211], v[0:3]
	v_mfma_f32_16x16x32_bf16 v[0:3], v[64:67], v[204:207], v[4:7]
	v_mfma_f32_16x16x32_bf16 v[72:75], v[68:71], v[164:167], v[72:75]
	v_mfma_f32_16x16x32_bf16 v[56:59], v[68:71], v[172:175], v[56:59]
	v_mfma_f32_16x16x32_bf16 v[40:43], v[68:71], v[200:203], v[40:43]
	v_mfma_f32_16x16x32_bf16 v[20:23], v[68:71], v[208:211], v[0:3]
	s_setprio 0
	s_setprio 1
	v_mfma_f32_16x16x32_bf16 v[0:3], v[144:147], v[160:163], v[8:11]
	v_mfma_f32_16x16x32_bf16 v[68:71], v[148:151], v[164:167], v[0:3]
	v_mfma_f32_16x16x32_bf16 v[0:3], v[152:155], v[160:163], v[12:15]
	v_mfma_f32_16x16x32_bf16 v[64:67], v[156:159], v[164:167], v[0:3]
	v_mfma_f32_16x16x32_bf16 v[0:3], v[144:147], v[168:171], v[52:55]
	v_mfma_f32_16x16x32_bf16 v[52:55], v[148:151], v[172:175], v[0:3]
	v_mfma_f32_16x16x32_bf16 v[0:3], v[152:155], v[168:171], v[48:51]
	v_mfma_f32_16x16x32_bf16 v[48:51], v[156:159], v[172:175], v[0:3]
	v_mfma_f32_16x16x32_bf16 v[0:3], v[144:147], v[196:199], v[36:39]
	v_mfma_f32_16x16x32_bf16 v[36:39], v[148:151], v[200:203], v[0:3]
	v_mfma_f32_16x16x32_bf16 v[0:3], v[152:155], v[196:199], v[32:35]
	v_mfma_f32_16x16x32_bf16 v[32:35], v[156:159], v[200:203], v[0:3]
	v_mfma_f32_16x16x32_bf16 v[0:3], v[144:147], v[204:207], v[24:27]
	v_mfma_f32_16x16x32_bf16 v[24:27], v[148:151], v[208:211], v[0:3]
	v_mfma_f32_16x16x32_bf16 v[0:3], v[152:155], v[204:207], v[16:19]
	v_mfma_f32_16x16x32_bf16 v[16:19], v[156:159], v[208:211], v[0:3]
	s_setprio 0
	s_barrier
	s_add_i32 s85, s85, 2
	s_add_u32 s54, s54, 0x100
	s_addc_u32 s55, s55, 0
	s_add_u32 s83, s83, 0x100
	s_addc_u32 s84, s84, 0
	s_cmp_gt_u32 s85, 13

; #define EPI_IT_ROW(it) EPI_ROW((it) >> 2, (it) & 3)
; #define EPI_LOAD_RR(ssp) float rr[8]; _Pragma("unroll") for (int it = 0; it < 8; ++it) rr[it] = (ssp)[EPI_IT_ROW(it)]; _Pragma("unroll") for (int it = 0; it < 8; ++it) rr[it] = rms_r(rr[it])
;     __device__ __forceinline__ void operator()(AccRef acc, const Unit& u, int wr, int wc, int fr, int fq) const {
;     ...
;         const bool rot = u.pn < 8; const int i0 = wc * 32 + 8 * fq;
;         EPI_LOAD_RR(ss);
;         if (rot) {
;             const float l2g = __builtin_amdgcn_logf(1.0f - __builtin_amdgcn_exp2f(-5.0f - (float)(u.pn & 3))) * (u.pn < 4 ? 1.f : -1.f);
; #pragma unroll
;             for (int it = 0; it < 8; ++it) rr[it] *= __builtin_amdgcn_exp2f((float)(EPI_IT_ROW(it) & 63) * l2g); }
.LBB0_1021:
	s_cmp_gt_i32 s52, 7
	s_cselect_b64 s[54:55], -1, 0
	s_lshl_b32 s6, s6, 8
	v_mov_b32_e32 v160, v227
	v_mov_b32_e32 v14, v228
	s_add_i32 s6, s6, s74
	s_and_b64 vcc, exec, s[54:55]
	v_add_u32_e32 v220, s6, v160
	v_ashrrev_i32_e32 v221, 31, v220
	v_add_u32_e32 v216, 16, v220
	v_add_u32_e32 v214, 32, v220
	v_add_u32_e32 v210, 48, v220
	v_add_u32_e32 v206, 0x80, v220
	v_lshl_add_u64 v[0:1], v[220:221], 2, s[10:11]
	v_ashrrev_i32_e32 v217, 31, v216
	v_ashrrev_i32_e32 v215, 31, v214
	v_ashrrev_i32_e32 v211, 31, v210
	v_ashrrev_i32_e32 v207, 31, v206
	v_add_u32_e32 v202, 0x90, v220
	v_add_u32_e32 v200, 0xa0, v220
	v_add_u32_e32 v196, 0xb0, v220
	v_mov_b32_e32 v15, v240
	v_lshl_add_u64 v[0:1], v[216:217], 2, s[10:11]
	v_lshl_add_u64 v[2:3], v[214:215], 2, s[10:11]
	v_lshl_add_u64 v[4:5], v[210:211], 2, s[10:11]
	v_lshl_add_u64 v[6:7], v[206:207], 2, s[10:11]
	v_ashrrev_i32_e32 v203, 31, v202
	v_ashrrev_i32_e32 v201, 31, v200
	v_ashrrev_i32_e32 v197, 31, v196
	v_lshl_add_u64 v[8:9], v[202:203], 2, s[10:11]
	v_lshl_add_u64 v[10:11], v[200:201], 2, s[10:11]
	v_lshl_add_u64 v[12:13], v[196:197], 2, s[10:11]
	v_mov_b32_e32 v0, v241
	s_nop 0
	v_mov_b32_e32 v1, v242
	s_nop 0
	v_mov_b32_e32 v2, v243
	v_mov_b32_e32 v3, v244
	s_nop 0
	v_mov_b32_e32 v4, v245
	v_mov_b32_e32 v5, v246
	v_mov_b32_e32 v6, v247
	v_lshl_add_u32 v222, v14, 3, s75
	s_mov_b64 s[6:7], -1
	v_ashrrev_i32_e32 v223, 31, v222
	s_nop 0
	v_fmamk_f32 v7, v15, 0x3a800000, v233
	v_rsq_f32_e32 v218, v7
	v_fmamk_f32 v0, v0, 0x3a800000, v233
	v_fmamk_f32 v1, v1, 0x3a800000, v233
	v_fmamk_f32 v2, v2, 0x3a800000, v233
	v_fmamk_f32 v3, v3, 0x3a800000, v233
	v_fmamk_f32 v4, v4, 0x3a800000, v233
	v_fmamk_f32 v5, v5, 0x3a800000, v233
	v_fmamk_f32 v6, v6, 0x3a800000, v233
	v_rsq_f32_e32 v219, v0
	v_rsq_f32_e32 v212, v1
	v_rsq_f32_e32 v213, v2
	v_rsq_f32_e32 v204, v3
	v_rsq_f32_e32 v205, v4
	v_rsq_f32_e32 v198, v5
	v_rsq_f32_e32 v199, v6
	s_cbranch_vccz .LBB0_1023
	s_mov_b64 s[6:7], 0

; #define PG8_STAGE(bufoff, gbase, voff) do { _Pragma("unroll") for (int _i = 0; _i < 2; ++_i) \
;         __builtin_amdgcn_global_load_lds((const unsigned*)((const char*)(gbase) + (voff)[_i]), (LAS unsigned*)(lds + (bufoff) + ldsw + _i * 8192), 16, 0, 0); } while (0)
; #define PG8_LDA(dst, b, h) do { _Pragma("unroll") for (int m = 0; m < 4; ++m) _Pragma("unroll") for (int k = 0; k < 2; ++k) dst[m][k] = *(const LAS bf16x8*)(lds + PG8_SA(b, h) + aoff + m * 2048 + k * 1024); } while (0)
; #define PG8_LDB(dst, b, h) do { _Pragma("unroll") for (int n = 0; n < 2; ++n) _Pragma("unroll") for (int k = 0; k < 2; ++k) dst[n][k] = *(const LAS bf16x8*)(lds + PG8_SB(b, h) + boff + n * 2048 + k * 1024); } while (0)
; #define PG8_MMA(ai, bj, At, Bt) do { __builtin_amdgcn_s_setprio(1); _Pragma("unroll") for (int m = 0; m < 4; ++m) _Pragma("unroll") for (int n = 0; n < 2; ++n) _Pragma("unroll") for (int k = 0; k < 2; ++k) \
;         acc[ai][bj][m][n] = __builtin_amdgcn_mfma_f32_16x16x32_bf16(Bt[n][k], At[m][k], acc[ai][bj][m][n], 0, 0, 0); __builtin_amdgcn_s_setprio(0); } while (0)
; #define PG8_BAR __builtin_amdgcn_s_barrier()
; template <class Epi>
; __device__ __forceinline__ void gemm_phase(LAS unsigned char* lds, const Gemm g, const StaticOrder& S, const Epi& E) {
;     ...
;         const bool has_next = S.next(ui + 1, nxt);
;         const char* nA = has_next ? (const char*)g.A + (size_t)nxt.pm * tstepA : cA; const char* nB = has_next ? (const char*)g.Bt + (size_t)nxt.pn * tstepB : cB;
; #pragma nounroll
;         for (int t = 0; t < nt; t += 2) {
;             const bool last = (t == nt - 2);
;             const char* a1 = cA + (size_t)(t + 1) * kstep;
;             const char* a2 = last ? nA : cA + (size_t)(t + 2) * kstep; const char* b2 = last ? nB : cB + (size_t)(t + 2) * kstep;
;             const char* a3 = a2 + kstep; const char* b3 = b2 + kstep;
;             PG8_LDB(B0, 0, 0); PG8_LDB(B1, 0, 1); PG8_SCHED; PG8_LDA(At, 0, 0); PG8_STAGE(PG8_SA(1, 1), a1 + hstepA, voffA);
;             PG8_WAIT_V(8); PG8_WAIT_L(0); PG8_BAR; PG8_MMA(0, 0, At, B0); PG8_MMA(0, 1, At, B1); PG8_BAR; PG8_SCHED;
;             PG8_LDA(At, 0, 1); PG8_STAGE(PG8_SB(0, 0), b2, voffB); PG8_STAGE(PG8_SB(0, 1), b2 + hstepB, voffB); PG8_STAGE(PG8_SA(0, 0), a2, voffA);
;             PG8_WAIT_V(8); PG8_WAIT_L(0); PG8_BAR; PG8_MMA(1, 0, At, B0); PG8_MMA(1, 1, At, B1); PG8_BAR; PG8_SCHED;
.LBB0_1402:
	s_ashr_i32 s69, s68, 31
	s_lshl_b64 s[12:13], s[68:69], 19
	s_add_u32 s70, s24, s12
	s_addc_u32 s71, s25, s13
	s_and_b64 s[12:13], s[4:5], exec
	s_cselect_b32 s1, s71, s9
	s_cselect_b32 s7, s70, s8
	s_ashr_i32 s65, s64, 31
	s_lshl_b64 s[12:13], s[64:65], 19
	s_add_u32 s72, s3, s12
	s_addc_u32 s73, s33, s13
	s_and_b64 s[12:13], s[4:5], exec
	s_cselect_b32 s65, s73, s11
	s_cselect_b32 s69, s72, s10
	s_add_u32 s8, s8, 0x40080
	s_addc_u32 s9, s9, 0
	s_add_u32 s74, s10, 0x100
	s_addc_u32 s75, s11, 0
	s_mov_b32 s87, -2
	v_lshl_add_u32 v248, s6, 8, v151
	v_add_u32_e32 v248, s63, v248
	v_ashrrev_i32_e32 v249, 31, v248
	v_lshl_add_u64 v[248:249], v[248:249], 2, s[18:19]
	global_load_dword v240, v[248:249], off
	global_load_dword v241, v[248:249], off offset:64
	global_load_dword v242, v[248:249], off offset:128
	global_load_dword v243, v[248:249], off offset:192
	global_load_dword v244, v[248:249], off offset:512
	global_load_dword v245, v[248:249], off offset:576
	global_load_dword v246, v[248:249], off offset:640
	global_load_dword v247, v[248:249], off offset:704
	ds_read_b128 v[146:149], v162
	ds_read_b128 v[166:169], v162 offset:1024
	ds_read_b128 v[170:173], v162 offset:2048
	ds_read_b128 v[178:181], v162 offset:3072
	ds_read_b128 v[182:185], v163
	ds_read_b128 v[186:189], v163 offset:1024
	ds_read_b128 v[190:193], v163 offset:2048
	ds_read_b128 v[194:197], v163 offset:3072
	s_add_u32 s10, s8, 0xfffc0080
	s_addc_u32 s11, s9, -1
	s_cmp_eq_u32 s87, 12
	s_cselect_b32 s13, s1, s11
	s_cselect_b32 s12, s7, s10
	s_cselect_b32 s11, s65, s75
	s_cselect_b32 s10, s69, s74
	v_lshl_add_u64 v[174:175], s[8:9], 0, v[138:139]
	s_add_i32 m0, s53, 0xc000
	ds_read_b128 v[198:201], v164
	ds_read_b128 v[202:205], v164 offset:1024
	ds_read_b128 v[206:209], v164 offset:2048
	ds_read_b128 v[210:213], v164 offset:3072
	ds_read_b128 v[214:217], v164 offset:4096
	ds_read_b128 v[218:221], v164 offset:5120
	ds_read_b128 v[222:225], v164 offset:6144
	ds_read_b128 v[226:229], v164 offset:7168
	global_load_lds_dwordx4 v[174:175], off
	v_lshl_add_u64 v[174:175], s[8:9], 0, v[140:141]
	s_add_i32 m0, s53, 0xe000
	s_nop 0
	global_load_lds_dwordx4 v[174:175], off
	s_waitcnt vmcnt(8)
	s_waitcnt lgkmcnt(0)
	s_barrier
	s_setprio 1
	s_waitcnt lgkmcnt(0)
	v_mfma_f32_16x16x32_bf16 v[124:127], v[146:149], v[198:201], 0
	v_mfma_f32_16x16x32_bf16 v[120:123], v[170:173], v[198:201], 0
	v_mfma_f32_16x16x32_bf16 v[112:115], v[146:149], v[206:209], 0
	v_mfma_f32_16x16x32_bf16 v[104:107], v[170:173], v[206:209], 0
	v_mfma_f32_16x16x32_bf16 v[100:103], v[146:149], v[214:217], 0
	v_mfma_f32_16x16x32_bf16 v[92:95], v[170:173], v[214:217], 0
	v_mfma_f32_16x16x32_bf16 v[84:87], v[146:149], v[222:225], 0
	v_mfma_f32_16x16x32_bf16 v[76:79], v[170:173], v[222:225], 0
	v_mfma_f32_16x16x32_bf16 v[124:127], v[166:169], v[202:205], v[124:127]
	v_mfma_f32_16x16x32_bf16 v[120:123], v[178:181], v[202:205], v[120:123]
	v_mfma_f32_16x16x32_bf16 v[112:115], v[166:169], v[210:213], v[112:115]
	v_mfma_f32_16x16x32_bf16 v[104:107], v[178:181], v[210:213], v[104:107]
	v_mfma_f32_16x16x32_bf16 v[100:103], v[166:169], v[218:221], v[100:103]
	v_mfma_f32_16x16x32_bf16 v[92:95], v[178:181], v[218:221], v[92:95]
	v_mfma_f32_16x16x32_bf16 v[84:87], v[166:169], v[226:229], v[84:87]
	v_mfma_f32_16x16x32_bf16 v[76:79], v[178:181], v[226:229], v[76:79]
	s_setprio 0
	s_setprio 1
	v_mfma_f32_16x16x32_bf16 v[116:119], v[182:185], v[198:201], 0
	v_mfma_f32_16x16x32_bf16 v[108:111], v[190:193], v[198:201], 0
	v_mfma_f32_16x16x32_bf16 v[96:99], v[182:185], v[206:209], 0
	v_mfma_f32_16x16x32_bf16 v[88:91], v[190:193], v[206:209], 0
	v_mfma_f32_16x16x32_bf16 v[80:83], v[182:185], v[214:217], 0
	v_mfma_f32_16x16x32_bf16 v[72:75], v[190:193], v[214:217], 0
	v_mfma_f32_16x16x32_bf16 v[68:71], v[182:185], v[222:225], 0
	v_mfma_f32_16x16x32_bf16 v[64:67], v[190:193], v[222:225], 0
	v_mfma_f32_16x16x32_bf16 v[116:119], v[186:189], v[202:205], v[116:119]
	v_mfma_f32_16x16x32_bf16 v[108:111], v[194:197], v[202:205], v[108:111]
	v_mfma_f32_16x16x32_bf16 v[96:99], v[186:189], v[210:213], v[96:99]
	v_mfma_f32_16x16x32_bf16 v[88:91], v[194:197], v[210:213], v[88:91]
	v_mfma_f32_16x16x32_bf16 v[80:83], v[186:189], v[218:221], v[80:83]
	v_mfma_f32_16x16x32_bf16 v[72:75], v[194:197], v[218:221], v[72:75]
	v_mfma_f32_16x16x32_bf16 v[68:71], v[186:189], v[226:229], v[68:71]
	v_mfma_f32_16x16x32_bf16 v[64:67], v[194:197], v[226:229], v[64:67]
	s_setprio 0
	s_barrier
	s_add_i32 s88, s83, s43
	v_lshl_add_u64 v[174:175], s[10:11], 0, v[130:131]
	s_mov_b32 m0, s88
	ds_read_b128 v[198:201], v164 offset:16384
	ds_read_b128 v[202:205], v164 offset:17408
	ds_read_b128 v[206:209], v164 offset:18432
	ds_read_b128 v[210:213], v164 offset:19456
	ds_read_b128 v[214:217], v164 offset:20480
	ds_read_b128 v[218:221], v164 offset:21504
	ds_read_b128 v[222:225], v164 offset:22528
	ds_read_b128 v[226:229], v164 offset:23552
	global_load_lds_dwordx4 v[174:175], off
	s_add_i32 m0, s88, 0x2000
	s_add_u32 s88, s10, 0x40000
	v_lshl_add_u64 v[230:231], s[10:11], 0, v[134:135]
	s_addc_u32 s89, s11, 0
	s_add_i32 s90, s84, s43
	global_load_lds_dwordx4 v[230:231], off
	v_lshl_add_u64 v[232:233], s[88:89], 0, v[130:131]
	s_mov_b32 m0, s90
	v_lshl_add_u64 v[234:235], s[12:13], 0, v[132:133]
	global_load_lds_dwordx4 v[232:233], off
	v_lshl_add_u64 v[232:233], s[88:89], 0, v[134:135]
	s_add_i32 m0, s90, 0x2000
	s_nop 0
	global_load_lds_dwordx4 v[232:233], off
	v_lshl_add_u64 v[232:233], s[12:13], 0, v[128:129]
	s_mov_b32 m0, s53
	s_nop 0
	global_load_lds_dwordx4 v[232:233], off
	s_mov_b32 m0, s55
	s_nop 0
	global_load_lds_dwordx4 v[234:235], off
	s_waitcnt vmcnt(8)
	s_waitcnt lgkmcnt(0)
	s_barrier
; #define PG8_STAGE(bufoff, gbase, voff) do { _Pragma("unroll") for (int _i = 0; _i < 2; ++_i) \
;         __builtin_amdgcn_global_load_lds((const unsigned*)((const char*)(gbase) + (voff)[_i]), (LAS unsigned*)(lds + (bufoff) + ldsw + _i * 8192), 16, 0, 0); } while (0)
; #define PG8_LDA(dst, b, h) do { _Pragma("unroll") for (int m = 0; m < 4; ++m) _Pragma("unroll") for (int k = 0; k < 2; ++k) dst[m][k] = *(const LAS bf16x8*)(lds + PG8_SA(b, h) + aoff + m * 2048 + k * 1024); } while (0)
; #define PG8_LDB(dst, b, h) do { _Pragma("unroll") for (int n = 0; n < 2; ++n) _Pragma("unroll") for (int k = 0; k < 2; ++k) dst[n][k] = *(const LAS bf16x8*)(lds + PG8_SB(b, h) + boff + n * 2048 + k * 1024); } while (0)
; #define PG8_MMA(ai, bj, At, Bt) do { __builtin_amdgcn_s_setprio(1); _Pragma("unroll") for (int m = 0; m < 4; ++m) _Pragma("unroll") for (int n = 0; n < 2; ++n) _Pragma("unroll") for (int k = 0; k < 2; ++k) \
;         acc[ai][bj][m][n] = __builtin_amdgcn_mfma_f32_16x16x32_bf16(Bt[n][k], At[m][k], acc[ai][bj][m][n], 0, 0, 0); __builtin_amdgcn_s_setprio(0); } while (0)
; #define PG8_WAIT_V(n) asm volatile("s_waitcnt vmcnt(" #n ")" ::: "memory")
; #define PG8_WAIT_L(n) asm volatile("s_waitcnt lgkmcnt(" #n ")" ::: "memory")
; #define PG8_BAR __builtin_amdgcn_s_barrier()
; #define PG8_SCHED __builtin_amdgcn_sched_barrier(0)
; template <class Epi>
; __device__ __forceinline__ void gemm_phase(LAS unsigned char* lds, const Gemm g, const StaticOrder& S, const Epi& E) {
;     ...
;             PG8_WAIT_V(8); PG8_WAIT_L(0); PG8_BAR; PG8_MMA(1, 0, At, B0); PG8_MMA(1, 1, At, B1); PG8_BAR; PG8_SCHED;
;             PG8_LDB(B0, 1, 0); PG8_LDB(B1, 1, 1); PG8_SCHED; PG8_LDA(At, 1, 0); PG8_STAGE(PG8_SA(0, 1), a2 + hstepA, voffA);
;             PG8_WAIT_V(8); PG8_WAIT_L(0); PG8_BAR; PG8_MMA(0, 0, At, B0); PG8_MMA(0, 1, At, B1); PG8_BAR; PG8_SCHED;
;             PG8_LDA(At, 1, 1); PG8_STAGE(PG8_SB(1, 0), b3, voffB); PG8_STAGE(PG8_SB(1, 1), b3 + hstepB, voffB); PG8_STAGE(PG8_SA(1, 0), a3, voffA);
	s_setprio 1
	s_waitcnt lgkmcnt(0)
	v_mfma_f32_16x16x32_bf16 v[60:63], v[146:149], v[198:201], 0
	v_mfma_f32_16x16x32_bf16 v[56:59], v[170:173], v[198:201], 0
	v_mfma_f32_16x16x32_bf16 v[52:55], v[146:149], v[206:209], 0
	v_mfma_f32_16x16x32_bf16 v[44:47], v[170:173], v[206:209], 0
	v_mfma_f32_16x16x32_bf16 v[36:39], v[146:149], v[214:217], 0
	v_mfma_f32_16x16x32_bf16 v[28:31], v[170:173], v[214:217], 0
	v_mfma_f32_16x16x32_bf16 v[20:23], v[146:149], v[222:225], 0
	v_mfma_f32_16x16x32_bf16 v[12:15], v[170:173], v[222:225], 0
	v_mfma_f32_16x16x32_bf16 v[60:63], v[166:169], v[202:205], v[60:63]
	v_mfma_f32_16x16x32_bf16 v[56:59], v[178:181], v[202:205], v[56:59]
	v_mfma_f32_16x16x32_bf16 v[52:55], v[166:169], v[210:213], v[52:55]
	v_mfma_f32_16x16x32_bf16 v[44:47], v[178:181], v[210:213], v[44:47]
	v_mfma_f32_16x16x32_bf16 v[36:39], v[166:169], v[218:221], v[36:39]
	v_mfma_f32_16x16x32_bf16 v[28:31], v[178:181], v[218:221], v[28:31]
	v_mfma_f32_16x16x32_bf16 v[20:23], v[166:169], v[226:229], v[20:23]
	v_mfma_f32_16x16x32_bf16 v[12:15], v[178:181], v[226:229], v[12:15]
	s_setprio 0
	s_setprio 1
	v_mfma_f32_16x16x32_bf16 v[48:51], v[182:185], v[198:201], 0
	v_mfma_f32_16x16x32_bf16 v[40:43], v[190:193], v[198:201], 0
	v_mfma_f32_16x16x32_bf16 v[32:35], v[182:185], v[206:209], 0
	v_mfma_f32_16x16x32_bf16 v[24:27], v[190:193], v[206:209], 0
	v_mfma_f32_16x16x32_bf16 v[16:19], v[182:185], v[214:217], 0
	v_mfma_f32_16x16x32_bf16 v[8:11], v[190:193], v[214:217], 0
	v_mfma_f32_16x16x32_bf16 v[4:7], v[182:185], v[222:225], 0
	v_mfma_f32_16x16x32_bf16 v[0:3], v[190:193], v[222:225], 0
	v_mfma_f32_16x16x32_bf16 v[48:51], v[186:189], v[202:205], v[48:51]
	v_mfma_f32_16x16x32_bf16 v[40:43], v[194:197], v[202:205], v[40:43]
	v_mfma_f32_16x16x32_bf16 v[32:35], v[186:189], v[210:213], v[32:35]
	v_mfma_f32_16x16x32_bf16 v[24:27], v[194:197], v[210:213], v[24:27]
	v_mfma_f32_16x16x32_bf16 v[16:19], v[186:189], v[218:221], v[16:19]
	v_mfma_f32_16x16x32_bf16 v[8:11], v[194:197], v[218:221], v[8:11]
	v_mfma_f32_16x16x32_bf16 v[4:7], v[186:189], v[226:229], v[4:7]
	v_mfma_f32_16x16x32_bf16 v[0:3], v[194:197], v[226:229], v[0:3]
	s_setprio 0
	s_barrier
	s_add_i32 s88, 0, 0x18000
	v_add_u32_e32 v136, s88, v161
	s_add_i32 s89, 0, 0x1c000
	ds_read_b128 v[146:149], v136
	ds_read_b128 v[166:169], v136 offset:1024
	ds_read_b128 v[170:173], v136 offset:2048
	ds_read_b128 v[178:181], v136 offset:3072
	v_add_u32_e32 v136, s89, v161
	ds_read_b128 v[182:185], v136
	ds_read_b128 v[186:189], v136 offset:1024
	ds_read_b128 v[190:193], v136 offset:2048
	ds_read_b128 v[194:197], v136 offset:3072
	s_add_u32 s12, s12, 0x40000
	s_addc_u32 s13, s13, 0
	s_mov_b32 m0, s57
	v_lshl_add_u64 v[236:237], s[12:13], 0, v[128:129]
	ds_read_b128 v[198:201], v164 offset:32768
	ds_read_b128 v[202:205], v164 offset:33792
	ds_read_b128 v[206:209], v164 offset:34816
	ds_read_b128 v[210:213], v164 offset:35840
	ds_read_b128 v[214:217], v164 offset:36864
	ds_read_b128 v[218:221], v164 offset:37888
	ds_read_b128 v[222:225], v164 offset:38912
	ds_read_b128 v[226:229], v164 offset:39936
	global_load_lds_dwordx4 v[236:237], off
	v_lshl_add_u64 v[236:237], s[12:13], 0, v[132:133]
	s_mov_b32 m0, s59
	s_nop 0
	global_load_lds_dwordx4 v[236:237], off
	s_waitcnt vmcnt(8)
	s_waitcnt lgkmcnt(0)
	s_barrier
	s_setprio 1
	s_waitcnt lgkmcnt(0)
	v_mfma_f32_16x16x32_bf16 v[124:127], v[146:149], v[198:201], v[124:127]
	v_mfma_f32_16x16x32_bf16 v[120:123], v[170:173], v[198:201], v[120:123]
	v_mfma_f32_16x16x32_bf16 v[112:115], v[146:149], v[206:209], v[112:115]
	v_mfma_f32_16x16x32_bf16 v[104:107], v[170:173], v[206:209], v[104:107]
	v_mfma_f32_16x16x32_bf16 v[100:103], v[146:149], v[214:217], v[100:103]
	v_mfma_f32_16x16x32_bf16 v[92:95], v[170:173], v[214:217], v[92:95]
	v_mfma_f32_16x16x32_bf16 v[84:87], v[146:149], v[222:225], v[84:87]
	v_mfma_f32_16x16x32_bf16 v[76:79], v[170:173], v[222:225], v[76:79]
	v_mfma_f32_16x16x32_bf16 v[124:127], v[166:169], v[202:205], v[124:127]
	v_mfma_f32_16x16x32_bf16 v[120:123], v[178:181], v[202:205], v[120:123]
	v_mfma_f32_16x16x32_bf16 v[112:115], v[166:169], v[210:213], v[112:115]
	v_mfma_f32_16x16x32_bf16 v[104:107], v[178:181], v[210:213], v[104:107]
	v_mfma_f32_16x16x32_bf16 v[100:103], v[166:169], v[218:221], v[100:103]
	v_mfma_f32_16x16x32_bf16 v[92:95], v[178:181], v[218:221], v[92:95]
	v_mfma_f32_16x16x32_bf16 v[84:87], v[166:169], v[226:229], v[84:87]
	v_mfma_f32_16x16x32_bf16 v[76:79], v[178:181], v[226:229], v[76:79]
	s_setprio 0
	s_setprio 1
	v_mfma_f32_16x16x32_bf16 v[116:119], v[182:185], v[198:201], v[116:119]
	v_mfma_f32_16x16x32_bf16 v[108:111], v[190:193], v[198:201], v[108:111]
	v_mfma_f32_16x16x32_bf16 v[96:99], v[182:185], v[206:209], v[96:99]
	v_mfma_f32_16x16x32_bf16 v[88:91], v[190:193], v[206:209], v[88:91]
	v_mfma_f32_16x16x32_bf16 v[80:83], v[182:185], v[214:217], v[80:83]
	v_mfma_f32_16x16x32_bf16 v[72:75], v[190:193], v[214:217], v[72:75]
	v_mfma_f32_16x16x32_bf16 v[68:71], v[182:185], v[222:225], v[68:71]
	v_mfma_f32_16x16x32_bf16 v[64:67], v[190:193], v[222:225], v[64:67]
	v_mfma_f32_16x16x32_bf16 v[116:119], v[186:189], v[202:205], v[116:119]
	v_mfma_f32_16x16x32_bf16 v[108:111], v[194:197], v[202:205], v[108:111]
	v_mfma_f32_16x16x32_bf16 v[96:99], v[186:189], v[210:213], v[96:99]
	v_mfma_f32_16x16x32_bf16 v[88:91], v[194:197], v[210:213], v[88:91]
	v_mfma_f32_16x16x32_bf16 v[80:83], v[186:189], v[218:221], v[80:83]
	v_mfma_f32_16x16x32_bf16 v[72:75], v[194:197], v[218:221], v[72:75]
	v_mfma_f32_16x16x32_bf16 v[68:71], v[186:189], v[226:229], v[68:71]
	v_mfma_f32_16x16x32_bf16 v[64:67], v[194:197], v[226:229], v[64:67]
	s_setprio 0
	s_barrier
; #define PG8_STAGE(bufoff, gbase, voff) do { _Pragma("unroll") for (int _i = 0; _i < 2; ++_i) \
;         __builtin_amdgcn_global_load_lds((const unsigned*)((const char*)(gbase) + (voff)[_i]), (LAS unsigned*)(lds + (bufoff) + ldsw + _i * 8192), 16, 0, 0); } while (0)
; #define PG8_LDA(dst, b, h) do { _Pragma("unroll") for (int m = 0; m < 4; ++m) _Pragma("unroll") for (int k = 0; k < 2; ++k) dst[m][k] = *(const LAS bf16x8*)(lds + PG8_SA(b, h) + aoff + m * 2048 + k * 1024); } while (0)
; #define PG8_LDB(dst, b, h) do { _Pragma("unroll") for (int n = 0; n < 2; ++n) _Pragma("unroll") for (int k = 0; k < 2; ++k) dst[n][k] = *(const LAS bf16x8*)(lds + PG8_SB(b, h) + boff + n * 2048 + k * 1024); } while (0)
; #define PG8_WAIT_V(n) asm volatile("s_waitcnt vmcnt(" #n ")" ::: "memory")
; #define PG8_WAIT_L(n) asm volatile("s_waitcnt lgkmcnt(" #n ")" ::: "memory")
; template <class Epi>
; __device__ __forceinline__ void gemm_phase(LAS unsigned char* lds, const Gemm g, const StaticOrder& S, const Epi& E) {
;     ...
;         for (int t = 0; t < nt; t += 2) {
;             const bool last = (t == nt - 2);
;             const char* a1 = cA + (size_t)(t + 1) * kstep;
;             const char* a2 = last ? nA : cA + (size_t)(t + 2) * kstep; const char* b2 = last ? nB : cB + (size_t)(t + 2) * kstep;
;             const char* a3 = a2 + kstep; const char* b3 = b2 + kstep;
;             PG8_LDB(B0, 0, 0); PG8_LDB(B1, 0, 1); PG8_SCHED; PG8_LDA(At, 0, 0); PG8_STAGE(PG8_SA(1, 1), a1 + hstepA, voffA);
;             PG8_WAIT_V(8); PG8_WAIT_L(0); PG8_BAR; PG8_MMA(0, 0, At, B0); PG8_MMA(0, 1, At, B1); PG8_BAR; PG8_SCHED;
;             PG8_LDA(At, 0, 1); PG8_STAGE(PG8_SB(0, 0), b2, voffB); PG8_STAGE(PG8_SB(0, 1), b2 + hstepB, voffB); PG8_STAGE(PG8_SA(0, 0), a2, voffA);
;             PG8_WAIT_V(8); PG8_WAIT_L(0); PG8_BAR; PG8_MMA(1, 0, At, B0); PG8_MMA(1, 1, At, B1); PG8_BAR; PG8_SCHED;
;             PG8_LDB(B0, 1, 0); PG8_LDB(B1, 1, 1); PG8_SCHED; PG8_LDA(At, 1, 0); PG8_STAGE(PG8_SA(0, 1), a2 + hstepA, voffA);
;             PG8_WAIT_V(8); PG8_WAIT_L(0); PG8_BAR; PG8_MMA(0, 0, At, B0); PG8_MMA(0, 1, At, B1); PG8_BAR; PG8_SCHED;
;             PG8_LDA(At, 1, 1); PG8_STAGE(PG8_SB(1, 0), b3, voffB); PG8_STAGE(PG8_SB(1, 1), b3 + hstepB, voffB); PG8_STAGE(PG8_SA(1, 0), a3, voffA);
;             PG8_WAIT_V(8); PG8_WAIT_L(0); PG8_BAR; PG8_MMA(1, 0, At, B0); PG8_MMA(1, 1, At, B1); PG8_BAR; PG8_SCHED;
	s_add_i32 s12, s88, s43
	v_lshl_add_u64 v[174:175], v[174:175], 0, s[34:35]
	s_mov_b32 m0, s12
	ds_read_b128 v[198:201], v164 offset:49152
	ds_read_b128 v[202:205], v164 offset:50176
	ds_read_b128 v[206:209], v164 offset:51200
	ds_read_b128 v[210:213], v164 offset:52224
	ds_read_b128 v[214:217], v164 offset:53248
	ds_read_b128 v[218:221], v164 offset:54272
	ds_read_b128 v[222:225], v164 offset:55296
	ds_read_b128 v[226:229], v164 offset:56320
	global_load_lds_dwordx4 v[174:175], off
	s_add_i32 m0, s12, 0x2000
	s_add_u32 s10, s10, 0x40080
	v_lshl_add_u64 v[174:175], v[230:231], 0, s[34:35]
	s_addc_u32 s11, s11, 0
	s_add_i32 s12, s89, s43
	global_load_lds_dwordx4 v[174:175], off
	v_lshl_add_u64 v[174:175], s[10:11], 0, v[130:131]
	s_mov_b32 m0, s12
	s_nop 0
	global_load_lds_dwordx4 v[174:175], off
	v_lshl_add_u64 v[174:175], s[10:11], 0, v[134:135]
	s_add_i32 m0, s12, 0x2000
	s_nop 0
	global_load_lds_dwordx4 v[174:175], off
	v_lshl_add_u64 v[174:175], v[232:233], 0, s[34:35]
	s_mov_b32 m0, s77
	s_nop 0
	global_load_lds_dwordx4 v[174:175], off
	v_lshl_add_u64 v[174:175], v[234:235], 0, s[34:35]
	s_mov_b32 m0, s78
	s_nop 0
	global_load_lds_dwordx4 v[174:175], off
	s_waitcnt vmcnt(8)
	s_waitcnt lgkmcnt(0)
	s_barrier
	s_setprio 1
	s_waitcnt lgkmcnt(0)
	v_mfma_f32_16x16x32_bf16 v[60:63], v[146:149], v[198:201], v[60:63]
	v_mfma_f32_16x16x32_bf16 v[56:59], v[170:173], v[198:201], v[56:59]
	v_mfma_f32_16x16x32_bf16 v[52:55], v[146:149], v[206:209], v[52:55]
	v_mfma_f32_16x16x32_bf16 v[44:47], v[170:173], v[206:209], v[44:47]
	v_mfma_f32_16x16x32_bf16 v[36:39], v[146:149], v[214:217], v[36:39]
	v_mfma_f32_16x16x32_bf16 v[28:31], v[170:173], v[214:217], v[28:31]
	v_mfma_f32_16x16x32_bf16 v[20:23], v[146:149], v[222:225], v[20:23]
	v_mfma_f32_16x16x32_bf16 v[12:15], v[170:173], v[222:225], v[12:15]
	v_mfma_f32_16x16x32_bf16 v[60:63], v[166:169], v[202:205], v[60:63]
	v_mfma_f32_16x16x32_bf16 v[56:59], v[178:181], v[202:205], v[56:59]
	v_mfma_f32_16x16x32_bf16 v[52:55], v[166:169], v[210:213], v[52:55]
	v_mfma_f32_16x16x32_bf16 v[44:47], v[178:181], v[210:213], v[44:47]
	v_mfma_f32_16x16x32_bf16 v[36:39], v[166:169], v[218:221], v[36:39]
	v_mfma_f32_16x16x32_bf16 v[28:31], v[178:181], v[218:221], v[28:31]
	v_mfma_f32_16x16x32_bf16 v[20:23], v[166:169], v[226:229], v[20:23]
	v_mfma_f32_16x16x32_bf16 v[12:15], v[178:181], v[226:229], v[12:15]
	s_setprio 0
	s_setprio 1
	v_mfma_f32_16x16x32_bf16 v[48:51], v[182:185], v[198:201], v[48:51]
	v_mfma_f32_16x16x32_bf16 v[40:43], v[190:193], v[198:201], v[40:43]
	v_mfma_f32_16x16x32_bf16 v[32:35], v[182:185], v[206:209], v[32:35]
	v_mfma_f32_16x16x32_bf16 v[24:27], v[190:193], v[206:209], v[24:27]
	v_mfma_f32_16x16x32_bf16 v[16:19], v[182:185], v[214:217], v[16:19]
	v_mfma_f32_16x16x32_bf16 v[8:11], v[190:193], v[214:217], v[8:11]
	v_mfma_f32_16x16x32_bf16 v[4:7], v[182:185], v[222:225], v[4:7]
	v_mfma_f32_16x16x32_bf16 v[0:3], v[190:193], v[222:225], v[0:3]
	v_mfma_f32_16x16x32_bf16 v[48:51], v[186:189], v[202:205], v[48:51]
	v_mfma_f32_16x16x32_bf16 v[40:43], v[194:197], v[202:205], v[40:43]
	v_mfma_f32_16x16x32_bf16 v[32:35], v[186:189], v[210:213], v[32:35]
	v_mfma_f32_16x16x32_bf16 v[24:27], v[194:197], v[210:213], v[24:27]
	v_mfma_f32_16x16x32_bf16 v[16:19], v[186:189], v[218:221], v[16:19]
	v_mfma_f32_16x16x32_bf16 v[8:11], v[194:197], v[218:221], v[8:11]
	v_mfma_f32_16x16x32_bf16 v[4:7], v[186:189], v[226:229], v[4:7]
	v_mfma_f32_16x16x32_bf16 v[0:3], v[194:197], v[226:229], v[0:3]
	s_setprio 0
	s_barrier
	s_add_i32 s87, s87, 2
	s_add_u32 s8, s8, 0x100
	s_addc_u32 s9, s9, 0
	s_add_u32 s74, s74, 0x100
	s_addc_u32 s75, s75, 0
	s_cmp_gt_u32 s87, 13

; __device__ __forceinline__ u32x2 pack4(f32x4 v) { return (u32x2){pk2(v[0], v[1]), pk2(v[2], v[3])}; }
; #define EPI_LOAD_RR(ssp) float rr[8]; _Pragma("unroll") for (int it = 0; it < 8; ++it) rr[it] = (ssp)[EPI_IT_ROW(it)]; _Pragma("unroll") for (int it = 0; it < 8; ++it) rr[it] = rms_r(rr[it])
;     __device__ __forceinline__ void operator()(AccRef acc, const Unit& u, int wr, int wc, int fr, int fq) const {
;         asm volatile("" : "+v"(fr), "+v"(fq));
;         const int j0 = u.pn * 128 + wc * 32 + 8 * fq;
;         u32x2 pa[2][2][4][2];
;         { EPI_LOAD_RR(ss);
; #pragma unroll
;           for (int it = 0; it < 8; ++it)
; #pragma unroll
;               for (int bj = 0; bj < 2; ++bj)
; #pragma unroll
;                   for (int n = 0; n < 2; ++n) pa[it >> 2][bj][it & 3][n] = pack4(acc[it >> 2][bj][it & 3][n] * rr[it]); }
.LBB0_1406:
	s_lshl_b32 s65, s6, 8
	v_mov_b32_e32 v166, v151
	v_mov_b32_e32 v185, v153
	s_add_i32 s65, s65, s63
	s_lshl_b32 s0, s0, 7
	v_add_u32_e32 v146, s65, v166
	v_ashrrev_i32_e32 v147, 31, v146
	v_lshl_add_u64 v[148:149], v[146:147], 2, s[18:19]
	v_mov_b32_e32 v136, v240
	v_add_u32_e32 v148, 16, v146
	v_add_u32_e32 v170, 32, v146
	v_ashrrev_i32_e32 v149, 31, v148
	v_ashrrev_i32_e32 v171, 31, v170
	v_add_u32_e32 v172, 48, v146
	v_add_u32_e32 v174, 0x80, v146
	v_add_u32_e32 v178, 0x90, v146
	v_add_u32_e32 v180, 0xa0, v146
	v_add_u32_e32 v182, 0xb0, v146
	v_lshl_add_u64 v[168:169], v[148:149], 2, s[18:19]
	v_lshl_add_u64 v[170:171], v[170:171], 2, s[18:19]
	v_ashrrev_i32_e32 v173, 31, v172
	v_ashrrev_i32_e32 v175, 31, v174
	v_ashrrev_i32_e32 v179, 31, v178
	v_ashrrev_i32_e32 v181, 31, v180
	v_ashrrev_i32_e32 v183, 31, v182
	v_lshl_add_u64 v[172:173], v[172:173], 2, s[18:19]
	v_lshl_add_u64 v[174:175], v[174:175], 2, s[18:19]
	v_lshl_add_u64 v[178:179], v[178:179], 2, s[18:19]
	v_lshl_add_u64 v[180:181], v[180:181], 2, s[18:19]
	v_lshl_add_u64 v[182:183], v[182:183], 2, s[18:19]
	v_mov_b32_e32 v147, v241
	v_mov_b32_e32 v149, v242
	v_mov_b32_e32 v150, v243
	v_mov_b32_e32 v152, v244
	v_mov_b32_e32 v167, v245
	s_nop 0
	v_mov_b32_e32 v169, v246
	v_mov_b32_e32 v170, v247
	s_or_b32 s0, s0, s76
	s_nop 0
	v_fmamk_f32 v136, v136, 0x3a800000, v165
	v_rsq_f32_e32 v168, v136
	v_fmamk_f32 v136, v147, 0x3a800000, v165
	v_fmamk_f32 v147, v149, 0x3a800000, v165
	v_fmamk_f32 v149, v150, 0x3a800000, v165
	v_fmamk_f32 v150, v152, 0x3a800000, v165
	v_fmamk_f32 v152, v167, 0x3a800000, v165
	v_fmamk_f32 v167, v169, 0x3a800000, v165
	v_fmamk_f32 v169, v170, 0x3a800000, v165
	v_rsq_f32_e32 v170, v136
	v_rsq_f32_e32 v180, v147
	v_rsq_f32_e32 v184, v150
	v_rsq_f32_e32 v150, v167
	v_rsq_f32_e32 v182, v149
	v_rsq_f32_e32 v152, v152
	v_rsq_f32_e32 v136, v169
	v_pk_mul_f32 v[108:109], v[108:109], v[168:169] op_sel_hi:[1,0]
	v_pk_mul_f32 v[122:123], v[122:123], v[168:169] op_sel_hi:[1,0]
	v_pk_mul_f32 v[116:117], v[116:117], v[168:169] op_sel_hi:[1,0]
	v_pk_mul_f32 v[110:111], v[110:111], v[168:169] op_sel_hi:[1,0]
	v_cvt_pk_bf16_f32 v171, v122, v123
	v_cvt_pk_bf16_f32 v181, v116, v117
	v_cvt_pk_bf16_f32 v173, v108, v109
	v_pk_mul_f32 v[42:43], v[42:43], v[184:185] op_sel_hi:[1,0]
	v_pk_mul_f32 v[108:109], v[114:115], v[170:171] op_sel_hi:[1,0]
	v_pk_mul_f32 v[104:105], v[104:105], v[170:171] op_sel_hi:[1,0]
	v_pk_mul_f32 v[80:81], v[80:81], v[180:181] op_sel_hi:[1,0]
	v_pk_mul_f32 v[72:73], v[72:73], v[180:181] op_sel_hi:[1,0]
	v_pk_mul_f32 v[10:11], v[10:11], v[150:151] op_sel_hi:[1,0]
	v_pk_mul_f32 v[8:9], v[8:9], v[150:151] op_sel_hi:[1,0]
	v_pk_mul_f32 v[118:119], v[118:119], v[168:169] op_sel_hi:[1,0]
	v_cvt_pk_bf16_f32 v174, v110, v111
	v_pk_mul_f32 v[110:111], v[112:113], v[170:171] op_sel_hi:[1,0]
	v_cvt_pk_bf16_f32 v183, v118, v119
	v_pk_mul_f32 v[106:107], v[106:107], v[170:171] op_sel_hi:[1,0]
	v_pk_mul_f32 v[98:99], v[98:99], v[170:171] op_sel_hi:[1,0]
	v_pk_mul_f32 v[96:97], v[96:97], v[170:171] op_sel_hi:[1,0]
	v_pk_mul_f32 v[90:91], v[90:91], v[170:171] op_sel_hi:[1,0]
	v_pk_mul_f32 v[88:89], v[88:89], v[170:171] op_sel_hi:[1,0]
	v_pk_mul_f32 v[112:113], v[94:95], v[180:181] op_sel_hi:[1,0]
	v_pk_mul_f32 v[114:115], v[92:93], v[180:181] op_sel_hi:[1,0]
	v_cvt_pk_bf16_f32 v93, v108, v109
	v_cvt_pk_bf16_f32 v170, v104, v105
	v_pk_mul_f32 v[82:83], v[82:83], v[180:181] op_sel_hi:[1,0]
	v_cvt_pk_bf16_f32 v95, v80, v81
	v_pk_mul_f32 v[74:75], v[74:75], v[180:181] op_sel_hi:[1,0]
	v_cvt_pk_bf16_f32 v80, v72, v73
	v_pk_mul_f32 v[72:73], v[86:87], v[182:183] op_sel_hi:[1,0]
	v_pk_mul_f32 v[40:41], v[40:41], v[184:185] op_sel_hi:[1,0]
	v_cvt_pk_bf16_f32 v105, v42, v43
	v_pk_mul_f32 v[42:43], v[52:53], v[152:153] op_sel_hi:[1,0]
	v_pk_mul_f32 v[26:27], v[26:27], v[152:153] op_sel_hi:[1,0]
	v_pk_mul_f32 v[24:25], v[24:25], v[152:153] op_sel_hi:[1,0]
	v_cvt_pk_bf16_f32 v108, v8, v9
	v_cvt_pk_bf16_f32 v109, v10, v11
	v_pk_mul_f32 v[8:9], v[22:23], v[136:137] op_sel_hi:[1,0]
	v_pk_mul_f32 v[10:11], v[20:21], v[136:137] op_sel_hi:[1,0]
	v_pk_mul_f32 v[126:127], v[126:127], v[168:169] op_sel_hi:[1,0]
	v_pk_mul_f32 v[124:125], v[124:125], v[168:169] op_sel_hi:[1,0]
	v_pk_mul_f32 v[120:121], v[120:121], v[168:169] op_sel_hi:[1,0]
	v_pk_mul_f32 v[102:103], v[102:103], v[180:181] op_sel_hi:[1,0]
	v_pk_mul_f32 v[100:101], v[100:101], v[180:181] op_sel_hi:[1,0]
	v_cvt_pk_bf16_f32 v169, v106, v107
	v_cvt_pk_bf16_f32 v168, v112, v113
	v_cvt_pk_bf16_f32 v178, v82, v83
	v_cvt_pk_bf16_f32 v81, v74, v75
	v_pk_mul_f32 v[74:75], v[84:85], v[182:183] op_sel_hi:[1,0]
	v_cvt_pk_bf16_f32 v83, v72, v73
	v_pk_mul_f32 v[72:73], v[78:79], v[182:183] op_sel_hi:[1,0]
	v_pk_mul_f32 v[50:51], v[50:51], v[184:185] op_sel_hi:[1,0]
; __device__ __forceinline__ f32x4 ror1v(f32x4 v) { return (f32x4){dpp_ror1(v[0]), dpp_ror1(v[1]), dpp_ror1(v[2]), dpp_ror1(v[3])}; }
; __device__ __forceinline__ f32x4 ror2v(f32x4 v) { return (f32x4){dpp_ror2(v[0]), dpp_ror2(v[1]), dpp_ror2(v[2]), dpp_ror2(v[3])}; }
; __device__ __forceinline__ u32x2 pack4(f32x4 v) { return (u32x2){pk2(v[0], v[1]), pk2(v[2], v[3])}; }
; __device__ __forceinline__ f32x4 unpack4(u32x2 w) { return (f32x4){bflo(w.x), bfhi(w.x), bflo(w.y), bfhi(w.y)}; }
;     __device__ __forceinline__ void operator()(AccRef acc, const Unit& u, int wr, int wc, int fr, int fq) const {
;     ...
;                   for (int n = 0; n < 2; ++n) pa[it >> 2][bj][it & 3][n] = pack4(acc[it >> 2][bj][it & 3][n] * rr[it]); }
;         __builtin_amdgcn_sched_barrier(0);
; #pragma unroll
;         for (int ai = 0; ai < 2; ++ai) {
;             const int rowg = u.pm * 256 + ai * 128 + wr * 64; const int grp = rowg >> 6;
; #pragma unroll
;             for (int n = 0; n < 2; ++n) { const unsigned jn = (unsigned)(j0 + 4 * n);
;                 f32x4 cu[4];
;                 {
;                     const f32x4 wu0 = *(const f32x4*)(cw + (DFF + jn)), wu1 = *(const f32x4*)(cw + (UPN + DFF + jn)), wu2 = *(const f32x4*)(cw + (2 * UPN + DFF + jn)), bu = *(const f32x4*)(cb + (DFF + jn));
;                     f32x4 pu1 = (f32x4){0.f, 0.f, 0.f, 0.f}, pu2 = pu1;
; #pragma unroll
;                     for (int m = 0; m < 4; ++m) {
;                         const f32x4 au = unpack4(pa[ai][1][m][n]);
;                         const f32x4 ru1 = ror1v(au), ru2 = ror2v(au);
;                         const f32x4 u1 = fr >= 1 ? ru1 : pu1, u2 = fr >= 2 ? ru2 : pu2;
;                         if (m == 0 && fr < 2) *(f32x4*)(edge + (unsigned)((grp * 4 + fr) * UPN + DFF + jn)) = au;
	v_pk_mul_f32 v[48:49], v[48:49], v[184:185] op_sel_hi:[1,0]
	v_cvt_pk_bf16_f32 v104, v40, v41
	v_pk_mul_f32 v[40:41], v[54:55], v[152:153] op_sel_hi:[1,0]
	v_cvt_pk_bf16_f32 v116, v42, v43
	v_pk_mul_f32 v[42:43], v[44:45], v[152:153] op_sel_hi:[1,0]
	v_cvt_pk_bf16_f32 v106, v24, v25
	v_cvt_pk_bf16_f32 v107, v26, v27
	v_pk_mul_f32 v[24:25], v[38:39], v[150:151] op_sel_hi:[1,0]
	v_pk_mul_f32 v[26:27], v[36:37], v[150:151] op_sel_hi:[1,0]
	v_cvt_pk_bf16_f32 v112, v10, v11
	v_cvt_pk_bf16_f32 v113, v8, v9
	v_pk_mul_f32 v[8:9], v[14:15], v[136:137] op_sel_hi:[1,0]
	v_pk_mul_f32 v[10:11], v[12:13], v[136:137] op_sel_hi:[1,0]
	v_pk_mul_f32 v[6:7], v[6:7], v[136:137] op_sel_hi:[1,0]
	v_pk_mul_f32 v[4:5], v[4:5], v[136:137] op_sel_hi:[1,0]
	v_pk_mul_f32 v[2:3], v[2:3], v[136:137] op_sel_hi:[1,0]
	v_pk_mul_f32 v[0:1], v[0:1], v[136:137] op_sel_hi:[1,0]
	v_lshl_add_u32 v44, v185, 3, s0
	v_cvt_pk_bf16_f32 v190, v124, v125
	v_cvt_pk_bf16_f32 v189, v126, v127
	v_cvt_pk_bf16_f32 v172, v120, v121
	v_cvt_pk_bf16_f32 v94, v110, v111
	v_cvt_pk_bf16_f32 v179, v96, v97
	v_cvt_pk_bf16_f32 v177, v98, v99
	v_cvt_pk_bf16_f32 v89, v88, v89
	v_cvt_pk_bf16_f32 v88, v90, v91
	v_cvt_pk_bf16_f32 v92, v100, v101
	v_cvt_pk_bf16_f32 v91, v102, v103
	v_cvt_pk_bf16_f32 v167, v114, v115
	v_cvt_pk_bf16_f32 v82, v74, v75
	v_pk_mul_f32 v[74:75], v[76:77], v[182:183] op_sel_hi:[1,0]
	v_cvt_pk_bf16_f32 v149, v72, v73
	v_pk_mul_f32 v[72:73], v[70:71], v[182:183] op_sel_hi:[1,0]
	v_cvt_pk_bf16_f32 v147, v74, v75
	v_pk_mul_f32 v[68:69], v[68:69], v[182:183] op_sel_hi:[1,0]
	v_cvt_pk_bf16_f32 v71, v72, v73
	v_pk_mul_f32 v[66:67], v[66:67], v[182:183] op_sel_hi:[1,0]
	v_cvt_pk_bf16_f32 v70, v68, v69
	v_pk_mul_f32 v[64:65], v[64:65], v[182:183] op_sel_hi:[1,0]
	v_cvt_pk_bf16_f32 v79, v66, v67
	v_pk_mul_f32 v[62:63], v[62:63], v[184:185] op_sel_hi:[1,0]
	v_cvt_pk_bf16_f32 v78, v64, v65
	v_pk_mul_f32 v[60:61], v[60:61], v[184:185] op_sel_hi:[1,0]
	v_cvt_pk_bf16_f32 v119, v62, v63
	v_pk_mul_f32 v[58:59], v[58:59], v[184:185] op_sel_hi:[1,0]
	v_cvt_pk_bf16_f32 v118, v60, v61
	v_pk_mul_f32 v[56:57], v[56:57], v[184:185] op_sel_hi:[1,0]
	v_cvt_pk_bf16_f32 v103, v58, v59
	v_cvt_pk_bf16_f32 v120, v48, v49
	v_cvt_pk_bf16_f32 v121, v50, v51
	v_cvt_pk_bf16_f32 v117, v40, v41
	v_pk_mul_f32 v[40:41], v[46:47], v[152:153] op_sel_hi:[1,0]
	v_cvt_pk_bf16_f32 v102, v56, v57
	v_cvt_pk_bf16_f32 v100, v42, v43
	v_pk_mul_f32 v[34:35], v[34:35], v[152:153] op_sel_hi:[1,0]
	v_cvt_pk_bf16_f32 v101, v40, v41
	v_pk_mul_f32 v[32:33], v[32:33], v[152:153] op_sel_hi:[1,0]
	v_cvt_pk_bf16_f32 v123, v34, v35
	v_cvt_pk_bf16_f32 v114, v26, v27
	v_cvt_pk_bf16_f32 v115, v24, v25
	v_pk_mul_f32 v[24:25], v[30:31], v[150:151] op_sel_hi:[1,0]
	v_cvt_pk_bf16_f32 v122, v32, v33
	v_pk_mul_f32 v[26:27], v[28:29], v[150:151] op_sel_hi:[1,0]
	v_cvt_pk_bf16_f32 v99, v24, v25
	v_pk_mul_f32 v[18:19], v[18:19], v[150:151] op_sel_hi:[1,0]
	v_cvt_pk_bf16_f32 v98, v26, v27
	v_pk_mul_f32 v[16:17], v[16:17], v[150:151] op_sel_hi:[1,0]
	v_cvt_pk_bf16_f32 v125, v18, v19
	v_cvt_pk_bf16_f32 v96, v10, v11
	v_cvt_pk_bf16_f32 v97, v8, v9
	v_cvt_pk_bf16_f32 v126, v4, v5
	v_cvt_pk_bf16_f32 v127, v6, v7
	s_nop 0
	v_cvt_pk_bf16_f32 v124, v16, v17
	v_cvt_pk_bf16_f32 v110, v0, v1
	v_cvt_pk_bf16_f32 v111, v2, v3
	v_add_u32_e32 v136, 0xb00, v44
	v_lshlrev_b64 v[12:13], 2, v[136:137]
	v_add_u32_e32 v136, 0x2100, v44
	v_lshl_add_u64 v[50:51], v[136:137], 2, s[20:21]
	v_add_u32_e32 v136, 0x3700, v44
	v_lshl_add_u64 v[48:49], s[20:21], 0, v[12:13]
	v_lshl_add_u64 v[52:53], v[136:137], 2, s[20:21]
	v_lshl_add_u64 v[54:55], s[22:23], 0, v[12:13]
	global_load_dwordx4 v[8:11], v[48:49], off
	global_load_dwordx4 v[0:3], v[50:51], off
	global_load_dwordx4 v[4:7], v[52:53], off
	global_load_dwordx4 v[12:15], v[54:55], off
	s_ashr_i32 s6, s65, 4
	v_add_u32_e32 v16, s6, v166
	v_mul_lo_u32 v175, v16, s85
	v_lshlrev_b32_e32 v36, 16, v181
	v_and_b32_e32 v37, 0xffff0000, v181
	v_lshlrev_b32_e32 v38, 16, v183
	v_and_b32_e32 v39, 0xffff0000, v183
	s_nop 1
	v_cmp_lt_i32_e64 s[10:11], 1, v166
	v_cmp_gt_i32_e64 s[12:13], 2, v166
	v_add_u32_e32 v84, 0xb00, v175
	v_mov_b32_dpp v191, v36 row_ror:1 row_mask:0xf bank_mask:0xf
	v_mov_b32_dpp v194, v37 row_ror:1 row_mask:0xf bank_mask:0xf
	v_mov_b32_dpp v192, v38 row_ror:1 row_mask:0xf bank_mask:0xf
	v_mov_b32_dpp v196, v39 row_ror:1 row_mask:0xf bank_mask:0xf
	v_mov_b32_dpp v193, v36 row_ror:2 row_mask:0xf bank_mask:0xf
	v_mov_b32_dpp v197, v37 row_ror:2 row_mask:0xf bank_mask:0xf
	v_mov_b32_dpp v201, v38 row_ror:2 row_mask:0xf bank_mask:0xf
	v_mov_b32_dpp v204, v39 row_ror:2 row_mask:0xf bank_mask:0xf
	s_and_saveexec_b64 s[0:1], s[12:13]
	s_cbranch_execz .LBB0_1408
	v_add_u32_e32 v136, v84, v44
	v_lshl_add_u64 v[16:17], v[136:137], 2, s[28:29]
	global_store_dwordx4 v[16:17], v[36:39], off
